# EpiResid epilogue (6 instances): second-half residual loads issued mid-first-half into own registers, copies at original sites, step waits recounted (vmcnt 31)
# speedup vs baseline: 1.0035x; 1.0035x over previous
; __device__ __forceinline__ float bf2f(unsigned h) { return __uint_as_float(h << 16); }
; __device__ __forceinline__ unsigned pk2(float lo, float hi) { f32x2 v = {lo, hi}; bf16x2_t b = __builtin_convertvector(v, bf16x2_t); return __builtin_bit_cast(unsigned, b); }
;     __device__ __forceinline__ void operator()(const f32x4 (&acc)[2][2][4][2], const Unit& u, int wr, int wc, int fr, int fq) const {
;     ...
;                 for (int m = 0; m < 4; ++m)
; #pragma unroll
;                     for (int bj = 0; bj < 2; ++bj)
; #pragma unroll
;                         for (int n = 0; n < 2; ++n) bsh[m][bj][n] = *(const u32x2*)(anp + (size_t)(ai * HALF + m * 16) * DM + bj * HALF + n * 16);
;             }
; #pragma unroll
;             for (int mp = 0; mp < 2; ++mp) {
;                 if (FROM_F32) {
; #pragma unroll
;                     for (int mm = 0; mm < 2; ++mm)
; #pragma unroll
;                         for (int bj = 0; bj < 2; ++bj)
; #pragma unroll
;                             for (int n = 0; n < 2; ++n) bsf[mm][bj][n] = *(const f32x4*)(basep + (size_t)(ai * HALF + (2 * mp + mm) * 16) * DM + bj * HALF + n * 16);
;                 }
; #pragma unroll
;                 for (int mm = 0; mm < 2; ++mm) {
;                     const int m = 2 * mp + mm; const size_t ro = (size_t)(ai * HALF + m * 16) * DM; float sq = 0.f;
; #pragma unroll
;                     for (int bj = 0; bj < 2; ++bj)
; #pragma unroll
;                         for (int n = 0; n < 2; ++n) {
;                             f32x4 xo;
;                             if (FROM_F32) xo = bsf[mm][bj][n];
;                             else { const u32x2 r_ = bsh[m][bj][n]; xo = (f32x4){bf2f(r_.x & 0xffff), bf2f(r_.x >> 16), bf2f(r_.y & 0xffff), bf2f(r_.y >> 16)} * rgv[bj][n]; }
;                             const f32x4 xn = xo + gvv[bj][n] * acc[ai][bj][m][n];
;                             sq += xn[0] * xn[0] + xn[1] * xn[1] + xn[2] * xn[2] + xn[3] * xn[3];
;                             if (HAS_AN) { const f32x4 hv = xn * gsv[bj][n]; u32x2 o; o.x = pk2(hv[0], hv[1]); o.y = pk2(hv[2], hv[3]); *(u32x2*)(anp + ro + bj * HALF + n * 16) = o; }
;                             else *(f32x4*)(outp + ro + bj * HALF + n * 16) = xn; }
;                     sq = rows_sum(sq);
;                     if (fq == (m & 3)) __hip_atomic_fetch_add(ssqp + ai * HALF + m * 16, sq, __ATOMIC_RELAXED, __HIP_MEMORY_SCOPE_AGENT);
.LBB0_367:
	s_or_b64 exec, exec, s[58:59]
	s_mov_b32 s101, 0
	s_mov_b32 s100, 0x40000
	v_lshl_add_u64 v[144:145], v[204:205], 0, s[100:101]
	global_load_dwordx2 v[146:147], v[144:145], off
	global_load_dwordx2 v[150:151], v[144:145], off offset:32
	global_load_dwordx2 v[152:153], v[144:145], off offset:256
	global_load_dwordx2 v[154:155], v[144:145], off offset:288
	s_mov_b32 s100, 0x48000
	v_lshl_add_u64 v[144:145], v[204:205], 0, s[100:101]
	global_load_dwordx2 v[156:157], v[144:145], off
	global_load_dwordx2 v[158:159], v[144:145], off offset:32
	global_load_dwordx2 v[222:223], v[144:145], off offset:256
	global_load_dwordx2 v[224:225], v[144:145], off offset:288
	s_mov_b32 s100, 0x50000
	v_lshl_add_u64 v[144:145], v[204:205], 0, s[100:101]
	global_load_dwordx2 v[226:227], v[144:145], off
	global_load_dwordx2 v[228:229], v[144:145], off offset:32
	global_load_dwordx2 v[230:231], v[144:145], off offset:256
	global_load_dwordx2 v[232:233], v[144:145], off offset:288
	s_mov_b32 s100, 0x58000
	v_lshl_add_u64 v[144:145], v[204:205], 0, s[100:101]
	global_load_dwordx2 v[234:235], v[144:145], off
	global_load_dwordx2 v[240:241], v[144:145], off offset:32
	global_load_dwordx2 v[242:243], v[144:145], off offset:256
	global_load_dwordx2 v[248:249], v[144:145], off offset:288
	s_waitcnt vmcnt(31)
	v_lshlrev_b32_e32 v136, 16, v220
	v_and_b32_e32 v137, 0xffff0000, v220
	v_pk_mul_f32 v[136:137], v[92:93], v[136:137]
	v_lshlrev_b32_e32 v138, 16, v221
	v_and_b32_e32 v139, 0xffff0000, v221
	v_pk_fma_f32 v[124:125], v[124:125], v[202:203], v[136:137]
	v_pk_mul_f32 v[138:139], v[94:95], v[138:139]
	v_mul_f32_e32 v136, v125, v125
	v_pk_fma_f32 v[126:127], v[126:127], v[200:201], v[138:139]
	v_fmac_f32_e32 v136, v124, v124
	v_fmac_f32_e32 v136, v126, v126
	s_mov_b64 s[20:21], 0x10000
	v_fmac_f32_e32 v136, v127, v127
	v_pk_mul_f32 v[126:127], v[78:79], v[126:127]
	v_pk_mul_f32 v[124:125], v[76:77], v[124:125]
	v_lshl_add_u64 v[128:129], v[204:205], 0, s[20:21]
	v_cvt_pk_bf16_f32 v124, v124, v125
	v_cvt_pk_bf16_f32 v125, v126, v127
	global_store_dwordx2 v[128:129], v[124:125], off
	s_waitcnt vmcnt(31)
	v_lshlrev_b32_e32 v124, 16, v218
	v_and_b32_e32 v125, 0xffff0000, v218
	v_pk_mul_f32 v[124:125], v[88:89], v[124:125]
	v_lshlrev_b32_e32 v126, 16, v219
	v_and_b32_e32 v127, 0xffff0000, v219
	v_pk_fma_f32 v[120:121], v[120:121], v[198:199], v[124:125]
	v_pk_mul_f32 v[126:127], v[90:91], v[126:127]
	v_mul_f32_e32 v124, v121, v121
	v_pk_fma_f32 v[122:123], v[122:123], v[196:197], v[126:127]
	v_fmac_f32_e32 v124, v120, v120
	v_fmac_f32_e32 v124, v122, v122
	s_mov_b64 s[20:21], 0x10020
	v_fmac_f32_e32 v124, v123, v123
	v_pk_mul_f32 v[122:123], v[70:71], v[122:123]
	v_pk_mul_f32 v[120:121], v[68:69], v[120:121]
	v_lshl_add_u64 v[130:131], v[204:205], 0, s[20:21]
	v_cvt_pk_bf16_f32 v120, v120, v121
	v_cvt_pk_bf16_f32 v121, v122, v123
	global_store_dwordx2 v[130:131], v[120:121], off
	s_waitcnt vmcnt(31)
	v_lshlrev_b32_e32 v120, 16, v216
	v_and_b32_e32 v121, 0xffff0000, v216
	v_pk_mul_f32 v[120:121], v[80:81], v[120:121]
	v_lshlrev_b32_e32 v122, 16, v217
	v_and_b32_e32 v123, 0xffff0000, v217
	v_pk_fma_f32 v[116:117], v[116:117], v[194:195], v[120:121]
	v_pk_mul_f32 v[122:123], v[82:83], v[122:123]
	v_mul_f32_e32 v120, v117, v117
	v_pk_fma_f32 v[118:119], v[118:119], v[192:193], v[122:123]
	v_fmac_f32_e32 v120, v116, v116
	v_fmac_f32_e32 v120, v118, v118
	s_mov_b64 s[20:21], 0x10100
	v_fmac_f32_e32 v120, v119, v119
	v_pk_mul_f32 v[118:119], v[66:67], v[118:119]
	v_pk_mul_f32 v[116:117], v[64:65], v[116:117]
	v_lshl_add_u64 v[132:133], v[204:205], 0, s[20:21]
	v_cvt_pk_bf16_f32 v116, v116, v117
	v_cvt_pk_bf16_f32 v117, v118, v119
	global_store_dwordx2 v[132:133], v[116:117], off
	s_waitcnt vmcnt(31)
	v_lshlrev_b32_e32 v116, 16, v212
	v_and_b32_e32 v117, 0xffff0000, v212
	v_pk_mul_f32 v[116:117], v[72:73], v[116:117]
	v_lshlrev_b32_e32 v118, 16, v213
	v_and_b32_e32 v119, 0xffff0000, v213
	v_pk_fma_f32 v[112:113], v[112:113], v[190:191], v[116:117]
	v_pk_mul_f32 v[118:119], v[74:75], v[118:119]
	v_mul_f32_e32 v116, v113, v113
	v_pk_fma_f32 v[114:115], v[114:115], v[188:189], v[118:119]
	v_fmac_f32_e32 v116, v112, v112
	v_add_f32_e32 v124, v136, v124
	v_fmac_f32_e32 v116, v114, v114
	s_mov_b64 s[20:21], 0x10120
	v_add_f32_e32 v120, v124, v120
	v_fmac_f32_e32 v116, v115, v115
	v_pk_mul_f32 v[114:115], v[62:63], v[114:115]
	v_pk_mul_f32 v[112:113], v[60:61], v[112:113]
	v_lshl_add_u64 v[134:135], v[204:205], 0, s[20:21]
	v_add_f32_e32 v116, v120, v116
	v_cvt_pk_bf16_f32 v112, v112, v113
	v_cvt_pk_bf16_f32 v113, v114, v115
	global_store_dwordx2 v[134:135], v[112:113], off
	v_mov_b32_e32 v112, v116
	s_nop 1
	v_permlane16_swap_b32_e32 v116, v112
	v_add_f32_e32 v112, v116, v112
	v_mov_b32_e32 v113, v112
	s_nop 1
	v_permlane32_swap_b32_e32 v112, v113
	s_and_saveexec_b64 s[58:59], s[8:9]
	s_cbranch_execz .LBB0_369
	v_add_f32_e32 v112, v112, v113
	global_atomic_add_f32 v[186:187], v112, off offset:128
; __device__ __forceinline__ float bf2f(unsigned h) { return __uint_as_float(h << 16); }
; __device__ __forceinline__ unsigned pk2(float lo, float hi) { f32x2 v = {lo, hi}; bf16x2_t b = __builtin_convertvector(v, bf16x2_t); return __builtin_bit_cast(unsigned, b); }
;     __device__ __forceinline__ void operator()(const f32x4 (&acc)[2][2][4][2], const Unit& u, int wr, int wc, int fr, int fq) const {
;     ...
;                 for (int m = 0; m < 4; ++m)
; #pragma unroll
;                     for (int bj = 0; bj < 2; ++bj)
; #pragma unroll
;                         for (int n = 0; n < 2; ++n) bsh[m][bj][n] = *(const u32x2*)(anp + (size_t)(ai * HALF + m * 16) * DM + bj * HALF + n * 16);
;             }
; #pragma unroll
;             for (int mp = 0; mp < 2; ++mp) {
;                 if (FROM_F32) {
; #pragma unroll
;                     for (int mm = 0; mm < 2; ++mm)
; #pragma unroll
;                         for (int bj = 0; bj < 2; ++bj)
; #pragma unroll
;                             for (int n = 0; n < 2; ++n) bsf[mm][bj][n] = *(const f32x4*)(basep + (size_t)(ai * HALF + (2 * mp + mm) * 16) * DM + bj * HALF + n * 16);
;                 }
; #pragma unroll
;                 for (int mm = 0; mm < 2; ++mm) {
;                     const int m = 2 * mp + mm; const size_t ro = (size_t)(ai * HALF + m * 16) * DM; float sq = 0.f;
; #pragma unroll
;                     for (int bj = 0; bj < 2; ++bj)
; #pragma unroll
;                         for (int n = 0; n < 2; ++n) {
;                             f32x4 xo;
;                             if (FROM_F32) xo = bsf[mm][bj][n];
;                             else { const u32x2 r_ = bsh[m][bj][n]; xo = (f32x4){bf2f(r_.x & 0xffff), bf2f(r_.x >> 16), bf2f(r_.y & 0xffff), bf2f(r_.y >> 16)} * rgv[bj][n]; }
;                             const f32x4 xn = xo + gvv[bj][n] * acc[ai][bj][m][n];
;                             sq += xn[0] * xn[0] + xn[1] * xn[1] + xn[2] * xn[2] + xn[3] * xn[3];
;                             if (HAS_AN) { const f32x4 hv = xn * gsv[bj][n]; u32x2 o; o.x = pk2(hv[0], hv[1]); o.y = pk2(hv[2], hv[3]); *(u32x2*)(anp + ro + bj * HALF + n * 16) = o; }
;                             else *(f32x4*)(outp + ro + bj * HALF + n * 16) = xn; }
;                     sq = rows_sum(sq);
;                     if (fq == (m & 3)) __hip_atomic_fetch_add(ssqp + ai * HALF + m * 16, sq, __ATOMIC_RELAXED, __HIP_MEMORY_SCOPE_AGENT);
.LBB0_369:
	s_or_b64 exec, exec, s[58:59]
	s_waitcnt vmcnt(31)
	v_lshlrev_b32_e32 v120, 16, v214
	v_and_b32_e32 v121, 0xffff0000, v214
	v_pk_mul_f32 v[120:121], v[92:93], v[120:121]
	v_lshlrev_b32_e32 v122, 16, v215
	v_and_b32_e32 v123, 0xffff0000, v215
	v_pk_fma_f32 v[108:109], v[108:109], v[202:203], v[120:121]
	v_pk_mul_f32 v[122:123], v[94:95], v[122:123]
	v_mul_f32_e32 v120, v109, v109
	v_pk_fma_f32 v[110:111], v[110:111], v[200:201], v[122:123]
	v_fmac_f32_e32 v120, v108, v108
	v_fmac_f32_e32 v120, v110, v110
	s_mov_b64 s[20:21], 0x18000
	v_fmac_f32_e32 v120, v111, v111
	v_pk_mul_f32 v[110:111], v[78:79], v[110:111]
	v_pk_mul_f32 v[108:109], v[76:77], v[108:109]
	v_lshl_add_u64 v[112:113], v[204:205], 0, s[20:21]
	v_cvt_pk_bf16_f32 v108, v108, v109
	v_cvt_pk_bf16_f32 v109, v110, v111
	global_store_dwordx2 v[112:113], v[108:109], off
	s_waitcnt vmcnt(31)
	v_lshlrev_b32_e32 v108, 16, v210
	v_and_b32_e32 v109, 0xffff0000, v210
	v_pk_mul_f32 v[108:109], v[88:89], v[108:109]
	v_lshlrev_b32_e32 v110, 16, v211
	v_and_b32_e32 v111, 0xffff0000, v211
	v_pk_fma_f32 v[104:105], v[104:105], v[198:199], v[108:109]
	v_pk_mul_f32 v[110:111], v[90:91], v[110:111]
	v_mul_f32_e32 v108, v105, v105
	v_pk_fma_f32 v[106:107], v[106:107], v[196:197], v[110:111]
	v_fmac_f32_e32 v108, v104, v104
	v_fmac_f32_e32 v108, v106, v106
	s_mov_b64 s[20:21], 0x18020
	v_fmac_f32_e32 v108, v107, v107
	v_pk_mul_f32 v[106:107], v[70:71], v[106:107]
	v_pk_mul_f32 v[104:105], v[68:69], v[104:105]
	v_lshl_add_u64 v[114:115], v[204:205], 0, s[20:21]
	v_cvt_pk_bf16_f32 v104, v104, v105
	v_cvt_pk_bf16_f32 v105, v106, v107
	global_store_dwordx2 v[114:115], v[104:105], off
	s_waitcnt vmcnt(31)
	v_lshlrev_b32_e32 v104, 16, v208
	v_and_b32_e32 v105, 0xffff0000, v208
	v_pk_mul_f32 v[104:105], v[80:81], v[104:105]
	v_lshlrev_b32_e32 v106, 16, v209
	v_and_b32_e32 v107, 0xffff0000, v209
	v_pk_fma_f32 v[100:101], v[100:101], v[194:195], v[104:105]
	v_pk_mul_f32 v[106:107], v[82:83], v[106:107]
	v_mul_f32_e32 v104, v101, v101
	v_pk_fma_f32 v[102:103], v[102:103], v[192:193], v[106:107]
	v_fmac_f32_e32 v104, v100, v100
	v_fmac_f32_e32 v104, v102, v102
	s_mov_b64 s[20:21], 0x18100
	v_fmac_f32_e32 v104, v103, v103
	v_pk_mul_f32 v[102:103], v[66:67], v[102:103]
	v_pk_mul_f32 v[100:101], v[64:65], v[100:101]
	v_lshl_add_u64 v[116:117], v[204:205], 0, s[20:21]
	v_cvt_pk_bf16_f32 v100, v100, v101
	v_cvt_pk_bf16_f32 v101, v102, v103
	global_store_dwordx2 v[116:117], v[100:101], off
	s_waitcnt vmcnt(31)
	v_lshlrev_b32_e32 v100, 16, v206
	v_and_b32_e32 v101, 0xffff0000, v206
	v_pk_mul_f32 v[100:101], v[72:73], v[100:101]
	v_lshlrev_b32_e32 v102, 16, v207
	v_and_b32_e32 v103, 0xffff0000, v207
	v_pk_fma_f32 v[96:97], v[96:97], v[190:191], v[100:101]
	v_pk_mul_f32 v[102:103], v[74:75], v[102:103]
	v_mul_f32_e32 v100, v97, v97
	v_pk_fma_f32 v[98:99], v[98:99], v[188:189], v[102:103]
	v_fmac_f32_e32 v100, v96, v96
	v_add_f32_e32 v108, v120, v108
	v_fmac_f32_e32 v100, v98, v98
	s_mov_b64 s[20:21], 0x18120
	v_add_f32_e32 v104, v108, v104
	v_fmac_f32_e32 v100, v99, v99
	v_pk_mul_f32 v[98:99], v[62:63], v[98:99]
	v_pk_mul_f32 v[96:97], v[60:61], v[96:97]
	v_lshl_add_u64 v[118:119], v[204:205], 0, s[20:21]
	v_add_f32_e32 v100, v104, v100
	v_cvt_pk_bf16_f32 v96, v96, v97
	v_cvt_pk_bf16_f32 v97, v98, v99
	global_store_dwordx2 v[118:119], v[96:97], off
	v_mov_b32_e32 v96, v100
	s_nop 1
	v_permlane16_swap_b32_e32 v100, v96
	v_add_f32_e32 v96, v100, v96
	v_mov_b32_e32 v97, v96
	s_nop 1
	v_permlane32_swap_b32_e32 v96, v97
	s_and_saveexec_b64 s[58:59], s[10:11]
	s_cbranch_execz .LBB0_371
	v_add_f32_e32 v96, v96, v97
	global_atomic_add_f32 v[186:187], v96, off offset:192
; __device__ __forceinline__ float bf2f(unsigned h) { return __uint_as_float(h << 16); }
;     __device__ __forceinline__ void operator()(const f32x4 (&acc)[2][2][4][2], const Unit& u, int wr, int wc, int fr, int fq) const {
;     ...
;             if (!FROM_F32) {
; #pragma unroll
;                 for (int m = 0; m < 4; ++m)
; #pragma unroll
;                     for (int bj = 0; bj < 2; ++bj)
; #pragma unroll
;                         for (int n = 0; n < 2; ++n) bsh[m][bj][n] = *(const u32x2*)(anp + (size_t)(ai * HALF + m * 16) * DM + bj * HALF + n * 16);
;             }
; #pragma unroll
;             for (int mp = 0; mp < 2; ++mp) {
;                 if (FROM_F32) {
; #pragma unroll
;                     for (int mm = 0; mm < 2; ++mm)
; #pragma unroll
;                         for (int bj = 0; bj < 2; ++bj)
; #pragma unroll
;                             for (int n = 0; n < 2; ++n) bsf[mm][bj][n] = *(const f32x4*)(basep + (size_t)(ai * HALF + (2 * mp + mm) * 16) * DM + bj * HALF + n * 16);
;                 }
; #pragma unroll
;                 for (int mm = 0; mm < 2; ++mm) {
;                     const int m = 2 * mp + mm; const size_t ro = (size_t)(ai * HALF + m * 16) * DM; float sq = 0.f;
; #pragma unroll
;                     for (int bj = 0; bj < 2; ++bj)
; #pragma unroll
;                         for (int n = 0; n < 2; ++n) {
;                             f32x4 xo;
;                             if (FROM_F32) xo = bsf[mm][bj][n];
;                             else { const u32x2 r_ = bsh[m][bj][n]; xo = (f32x4){bf2f(r_.x & 0xffff), bf2f(r_.x >> 16), bf2f(r_.y & 0xffff), bf2f(r_.y >> 16)} * rgv[bj][n]; }
;                             const f32x4 xn = xo + gvv[bj][n] * acc[ai][bj][m][n];
;                             sq += xn[0] * xn[0] + xn[1] * xn[1] + xn[2] * xn[2] + xn[3] * xn[3];
;                             if (HAS_AN) { const f32x4 hv = xn * gsv[bj][n]; u32x2 o; o.x = pk2(hv[0], hv[1]); o.y = pk2(hv[2], hv[3]); *(u32x2*)(anp + ro + bj * HALF + n * 16) = o; }
;                             else *(f32x4*)(outp + ro + bj * HALF + n * 16) = xn; }
;                     sq = rows_sum(sq);
;                     if (fq == (m & 3)) __hip_atomic_fetch_add(ssqp + ai * HALF + m * 16, sq, __ATOMIC_RELAXED, __HIP_MEMORY_SCOPE_AGENT);
.LBB0_371:
	s_or_b64 exec, exec, s[58:59]
	v_add_co_u32_e32 v120, vcc, 0x40000, v204
	s_nop 1
	v_addc_co_u32_e32 v121, vcc, 0, v205, vcc
	s_waitcnt vmcnt(8)
	v_mov_b32_e32 v126, v146
	v_mov_b32_e32 v127, v147
	v_mov_b32_e32 v128, v150
	v_mov_b32_e32 v129, v151
	v_mov_b32_e32 v124, v152
	v_mov_b32_e32 v125, v153
	v_mov_b32_e32 v122, v154
	v_mov_b32_e32 v123, v155
	v_add_co_u32_e32 v96, vcc, 0x48000, v204
	v_lshlrev_b32_e32 v130, 16, v126
	v_addc_co_u32_e32 v97, vcc, 0, v205, vcc
	v_mov_b32_e32 v118, v156
	v_mov_b32_e32 v119, v157
	v_mov_b32_e32 v116, v158
	v_mov_b32_e32 v117, v159
	v_mov_b32_e32 v114, v222
	v_mov_b32_e32 v115, v223
	v_mov_b32_e32 v112, v224
	v_mov_b32_e32 v113, v225
	v_add_co_u32_e32 v96, vcc, 0x50000, v204
	v_and_b32_e32 v131, 0xffff0000, v126
	s_nop 0
	v_addc_co_u32_e32 v97, vcc, 0, v205, vcc
	v_mov_b32_e32 v110, v226
	v_mov_b32_e32 v111, v227
	v_mov_b32_e32 v108, v228
	v_mov_b32_e32 v109, v229
	v_mov_b32_e32 v106, v230
	v_mov_b32_e32 v107, v231
	v_mov_b32_e32 v104, v232
	v_mov_b32_e32 v105, v233
	v_add_co_u32_e32 v96, vcc, 0x58000, v204
	v_lshlrev_b32_e32 v126, 16, v127
	s_nop 0
	v_addc_co_u32_e32 v97, vcc, 0, v205, vcc
	v_mov_b32_e32 v102, v234
	v_mov_b32_e32 v103, v235
	v_mov_b32_e32 v100, v240
	v_mov_b32_e32 v101, v241
	v_mov_b32_e32 v98, v242
	v_mov_b32_e32 v99, v243
	s_nop 0
	v_mov_b32_e32 v96, v248
	v_mov_b32_e32 v97, v249
	v_and_b32_e32 v127, 0xffff0000, v127
	v_pk_mul_f32 v[130:131], v[92:93], v[130:131]
	v_pk_mul_f32 v[126:127], v[94:95], v[126:127]
	v_pk_fma_f32 v[84:85], v[84:85], v[202:203], v[130:131]
	v_pk_fma_f32 v[86:87], v[86:87], v[200:201], v[126:127]
	v_mul_f32_e32 v126, v85, v85
	v_fmac_f32_e32 v126, v84, v84
	v_fmac_f32_e32 v126, v86, v86
	v_fmac_f32_e32 v126, v87, v87
	v_pk_mul_f32 v[86:87], v[78:79], v[86:87]
	v_pk_mul_f32 v[84:85], v[76:77], v[84:85]
	s_nop 0
	v_cvt_pk_bf16_f32 v84, v84, v85
	v_cvt_pk_bf16_f32 v85, v86, v87
	global_store_dwordx2 v[120:121], v[84:85], off
	s_waitcnt vmcnt(15)
	v_lshlrev_b32_e32 v84, 16, v128
	v_and_b32_e32 v85, 0xffff0000, v128
	v_pk_mul_f32 v[84:85], v[88:89], v[84:85]
	v_lshlrev_b32_e32 v86, 16, v129
	v_and_b32_e32 v87, 0xffff0000, v129
	v_pk_fma_f32 v[56:57], v[56:57], v[198:199], v[84:85]
	v_pk_mul_f32 v[86:87], v[90:91], v[86:87]
	v_mul_f32_e32 v84, v57, v57
	v_pk_fma_f32 v[58:59], v[58:59], v[196:197], v[86:87]
	v_fmac_f32_e32 v84, v56, v56
	v_fmac_f32_e32 v84, v58, v58
	v_fmac_f32_e32 v84, v59, v59
	v_pk_mul_f32 v[58:59], v[70:71], v[58:59]
	v_pk_mul_f32 v[56:57], v[68:69], v[56:57]
	v_add_f32_e32 v84, v126, v84
	v_cvt_pk_bf16_f32 v56, v56, v57
	v_cvt_pk_bf16_f32 v57, v58, v59
	global_store_dwordx2 v[120:121], v[56:57], off offset:32
	s_waitcnt vmcnt(15)
	v_lshlrev_b32_e32 v56, 16, v124
	v_and_b32_e32 v57, 0xffff0000, v124
	v_pk_mul_f32 v[56:57], v[80:81], v[56:57]
	v_lshlrev_b32_e32 v58, 16, v125
	v_and_b32_e32 v59, 0xffff0000, v125
	v_pk_fma_f32 v[52:53], v[52:53], v[194:195], v[56:57]
	v_pk_mul_f32 v[58:59], v[82:83], v[58:59]
	v_mul_f32_e32 v56, v53, v53
	v_pk_fma_f32 v[54:55], v[54:55], v[192:193], v[58:59]
	v_fmac_f32_e32 v56, v52, v52
	v_fmac_f32_e32 v56, v54, v54
	v_fmac_f32_e32 v56, v55, v55
	v_pk_mul_f32 v[54:55], v[66:67], v[54:55]
	v_pk_mul_f32 v[52:53], v[64:65], v[52:53]
	v_add_f32_e32 v56, v84, v56
	v_cvt_pk_bf16_f32 v52, v52, v53
	v_cvt_pk_bf16_f32 v53, v54, v55
	global_store_dwordx2 v[120:121], v[52:53], off offset:256
	s_waitcnt vmcnt(15)
	v_lshlrev_b32_e32 v52, 16, v122
	v_and_b32_e32 v53, 0xffff0000, v122
	v_pk_mul_f32 v[52:53], v[72:73], v[52:53]
	v_lshlrev_b32_e32 v54, 16, v123
	v_and_b32_e32 v55, 0xffff0000, v123
	v_pk_fma_f32 v[48:49], v[48:49], v[190:191], v[52:53]
	v_pk_mul_f32 v[54:55], v[74:75], v[54:55]
	v_mul_f32_e32 v52, v49, v49
	v_pk_fma_f32 v[50:51], v[50:51], v[188:189], v[54:55]
	v_fmac_f32_e32 v52, v48, v48
	v_fmac_f32_e32 v52, v50, v50
	v_fmac_f32_e32 v52, v51, v51
	v_pk_mul_f32 v[50:51], v[62:63], v[50:51]
	v_pk_mul_f32 v[48:49], v[60:61], v[48:49]
	v_add_f32_e32 v52, v56, v52
	v_cvt_pk_bf16_f32 v48, v48, v49
	v_cvt_pk_bf16_f32 v49, v50, v51
	global_store_dwordx2 v[120:121], v[48:49], off offset:288
	v_mov_b32_e32 v48, v52
	s_nop 1
	v_permlane16_swap_b32_e32 v52, v48
	v_add_f32_e32 v48, v52, v48
	v_mov_b32_e32 v49, v48
	s_nop 1
	v_permlane32_swap_b32_e32 v48, v49
	s_and_saveexec_b64 s[58:59], s[4:5]
	s_cbranch_execz .LBB0_373
	v_add_f32_e32 v48, v48, v49
	global_atomic_add_f32 v[186:187], v48, off offset:512

; __device__ __forceinline__ float bf2f(unsigned h) { return __uint_as_float(h << 16); }
; __device__ __forceinline__ unsigned pk2(float lo, float hi) { f32x2 v = {lo, hi}; bf16x2_t b = __builtin_convertvector(v, bf16x2_t); return __builtin_bit_cast(unsigned, b); }
;     __device__ __forceinline__ void operator()(const f32x4 (&acc)[2][2][4][2], const Unit& u, int wr, int wc, int fr, int fq) const {
;     ...
;                 for (int m = 0; m < 4; ++m)
; #pragma unroll
;                     for (int bj = 0; bj < 2; ++bj)
; #pragma unroll
;                         for (int n = 0; n < 2; ++n) bsh[m][bj][n] = *(const u32x2*)(anp + (size_t)(ai * HALF + m * 16) * DM + bj * HALF + n * 16);
;             }
; #pragma unroll
;             for (int mp = 0; mp < 2; ++mp) {
;                 if (FROM_F32) {
; #pragma unroll
;                     for (int mm = 0; mm < 2; ++mm)
; #pragma unroll
;                         for (int bj = 0; bj < 2; ++bj)
; #pragma unroll
;                             for (int n = 0; n < 2; ++n) bsf[mm][bj][n] = *(const f32x4*)(basep + (size_t)(ai * HALF + (2 * mp + mm) * 16) * DM + bj * HALF + n * 16);
;                 }
; #pragma unroll
;                 for (int mm = 0; mm < 2; ++mm) {
;                     const int m = 2 * mp + mm; const size_t ro = (size_t)(ai * HALF + m * 16) * DM; float sq = 0.f;
; #pragma unroll
;                     for (int bj = 0; bj < 2; ++bj)
; #pragma unroll
;                         for (int n = 0; n < 2; ++n) {
;                             f32x4 xo;
;                             if (FROM_F32) xo = bsf[mm][bj][n];
;                             else { const u32x2 r_ = bsh[m][bj][n]; xo = (f32x4){bf2f(r_.x & 0xffff), bf2f(r_.x >> 16), bf2f(r_.y & 0xffff), bf2f(r_.y >> 16)} * rgv[bj][n]; }
;                             const f32x4 xn = xo + gvv[bj][n] * acc[ai][bj][m][n];
;                             sq += xn[0] * xn[0] + xn[1] * xn[1] + xn[2] * xn[2] + xn[3] * xn[3];
;                             if (HAS_AN) { const f32x4 hv = xn * gsv[bj][n]; u32x2 o; o.x = pk2(hv[0], hv[1]); o.y = pk2(hv[2], hv[3]); *(u32x2*)(anp + ro + bj * HALF + n * 16) = o; }
;                             else *(f32x4*)(outp + ro + bj * HALF + n * 16) = xn; }
;                     sq = rows_sum(sq);
;                     if (fq == (m & 3)) __hip_atomic_fetch_add(ssqp + ai * HALF + m * 16, sq, __ATOMIC_RELAXED, __HIP_MEMORY_SCOPE_AGENT);
.LBB0_912:
	s_or_b64 exec, exec, s[58:59]
	s_mov_b32 s101, 0
	s_mov_b32 s100, 0x40000
	v_lshl_add_u64 v[156:157], v[206:207], 0, s[100:101]
	global_load_dwordx2 v[158:159], v[156:157], off
	global_load_dwordx2 v[160:161], v[156:157], off offset:32
	global_load_dwordx2 v[162:163], v[156:157], off offset:256
	global_load_dwordx2 v[164:165], v[156:157], off offset:288
	s_mov_b32 s100, 0x48000
	v_lshl_add_u64 v[156:157], v[206:207], 0, s[100:101]
	global_load_dwordx2 v[166:167], v[156:157], off
	global_load_dwordx2 v[168:169], v[156:157], off offset:32
	global_load_dwordx2 v[170:171], v[156:157], off offset:256
	global_load_dwordx2 v[172:173], v[156:157], off offset:288
	s_mov_b32 s100, 0x50000
	v_lshl_add_u64 v[156:157], v[206:207], 0, s[100:101]
	global_load_dwordx2 v[174:175], v[156:157], off
	global_load_dwordx2 v[224:225], v[156:157], off offset:32
	global_load_dwordx2 v[228:229], v[156:157], off offset:256
	global_load_dwordx2 v[232:233], v[156:157], off offset:288
	s_mov_b32 s100, 0x58000
	v_lshl_add_u64 v[156:157], v[206:207], 0, s[100:101]
	global_load_dwordx2 v[234:235], v[156:157], off
	global_load_dwordx2 v[236:237], v[156:157], off offset:32
	global_load_dwordx2 v[240:241], v[156:157], off offset:256
	global_load_dwordx2 v[242:243], v[156:157], off offset:288
	v_lshlrev_b32_e32 v152, 16, v222
	v_and_b32_e32 v153, 0xffff0000, v222
	v_pk_mul_f32 v[152:153], v[108:109], v[152:153]
	v_lshlrev_b32_e32 v154, 16, v223
	v_and_b32_e32 v155, 0xffff0000, v223
	v_pk_fma_f32 v[140:141], v[140:141], v[100:101], v[152:153]
	v_pk_mul_f32 v[154:155], v[110:111], v[154:155]
	v_mul_f32_e32 v152, v141, v141
	v_pk_fma_f32 v[142:143], v[142:143], v[102:103], v[154:155]
	v_fmac_f32_e32 v152, v140, v140
	v_fmac_f32_e32 v152, v142, v142
	s_mov_b64 s[46:47], 0x10000
	v_fmac_f32_e32 v152, v143, v143
	v_pk_mul_f32 v[142:143], v[98:99], v[142:143]
	v_pk_mul_f32 v[140:141], v[96:97], v[140:141]
	v_lshl_add_u64 v[144:145], v[206:207], 0, s[46:47]
	v_cvt_pk_bf16_f32 v140, v140, v141
	v_cvt_pk_bf16_f32 v141, v142, v143
	global_store_dwordx2 v[144:145], v[140:141], off
	v_lshlrev_b32_e32 v140, 16, v220
	v_and_b32_e32 v141, 0xffff0000, v220
	v_pk_mul_f32 v[140:141], v[92:93], v[140:141]
	v_lshlrev_b32_e32 v142, 16, v221
	v_and_b32_e32 v143, 0xffff0000, v221
	v_pk_fma_f32 v[136:137], v[136:137], v[88:89], v[140:141]
	v_pk_mul_f32 v[142:143], v[94:95], v[142:143]
	v_mul_f32_e32 v140, v137, v137
	v_pk_fma_f32 v[138:139], v[138:139], v[90:91], v[142:143]
	v_fmac_f32_e32 v140, v136, v136
	v_fmac_f32_e32 v140, v138, v138
	s_mov_b64 s[46:47], 0x10020
	v_fmac_f32_e32 v140, v139, v139
	v_pk_mul_f32 v[138:139], v[86:87], v[138:139]
	v_pk_mul_f32 v[136:137], v[84:85], v[136:137]
	v_lshl_add_u64 v[146:147], v[206:207], 0, s[46:47]
	v_cvt_pk_bf16_f32 v136, v136, v137
	v_cvt_pk_bf16_f32 v137, v138, v139
	global_store_dwordx2 v[146:147], v[136:137], off
	v_lshlrev_b32_e32 v136, 16, v218
	v_and_b32_e32 v137, 0xffff0000, v218
	v_pk_mul_f32 v[136:137], v[80:81], v[136:137]
	v_lshlrev_b32_e32 v138, 16, v219
	v_and_b32_e32 v139, 0xffff0000, v219
	v_pk_fma_f32 v[132:133], v[132:133], v[76:77], v[136:137]
	v_pk_mul_f32 v[138:139], v[82:83], v[138:139]
	v_mul_f32_e32 v136, v133, v133
	v_pk_fma_f32 v[134:135], v[134:135], v[78:79], v[138:139]
	v_fmac_f32_e32 v136, v132, v132
	v_fmac_f32_e32 v136, v134, v134
	s_mov_b64 s[46:47], 0x10100
	v_fmac_f32_e32 v136, v135, v135
	v_pk_mul_f32 v[134:135], v[74:75], v[134:135]
	v_pk_mul_f32 v[132:133], v[72:73], v[132:133]
	v_lshl_add_u64 v[148:149], v[206:207], 0, s[46:47]
	v_cvt_pk_bf16_f32 v132, v132, v133
	v_cvt_pk_bf16_f32 v133, v134, v135
	global_store_dwordx2 v[148:149], v[132:133], off
	v_lshlrev_b32_e32 v132, 16, v214
	v_and_b32_e32 v133, 0xffff0000, v214
	v_pk_mul_f32 v[132:133], v[68:69], v[132:133]
	v_lshlrev_b32_e32 v134, 16, v215
	v_and_b32_e32 v135, 0xffff0000, v215
	v_pk_fma_f32 v[128:129], v[128:129], v[64:65], v[132:133]
	v_pk_mul_f32 v[134:135], v[70:71], v[134:135]
	v_mul_f32_e32 v132, v129, v129
	v_pk_fma_f32 v[130:131], v[130:131], v[66:67], v[134:135]
	v_fmac_f32_e32 v132, v128, v128
	v_add_f32_e32 v140, v152, v140
	v_fmac_f32_e32 v132, v130, v130
	s_mov_b64 s[46:47], 0x10120
	v_add_f32_e32 v136, v140, v136
	v_fmac_f32_e32 v132, v131, v131
	v_pk_mul_f32 v[130:131], v[62:63], v[130:131]
	v_pk_mul_f32 v[128:129], v[60:61], v[128:129]
	v_lshl_add_u64 v[150:151], v[206:207], 0, s[46:47]
	v_add_f32_e32 v132, v136, v132
	v_cvt_pk_bf16_f32 v128, v128, v129
	v_cvt_pk_bf16_f32 v129, v130, v131
	global_store_dwordx2 v[150:151], v[128:129], off
	v_mov_b32_e32 v128, v132
	s_nop 1
	v_permlane16_swap_b32_e32 v132, v128
	v_add_f32_e32 v128, v132, v128
	v_mov_b32_e32 v129, v128
	s_nop 1
	v_permlane32_swap_b32_e32 v128, v129
	s_and_saveexec_b64 s[58:59], s[12:13]
	s_cbranch_execz .LBB0_914
	v_add_f32_e32 v128, v128, v129
	global_atomic_add_f32 v[204:205], v128, off offset:128

; __device__ __forceinline__ float bf2f(unsigned h) { return __uint_as_float(h << 16); }
;     __device__ __forceinline__ void operator()(const f32x4 (&acc)[2][2][4][2], const Unit& u, int wr, int wc, int fr, int fq) const {
;     ...
;             if (!FROM_F32) {
; #pragma unroll
;                 for (int m = 0; m < 4; ++m)
; #pragma unroll
;                     for (int bj = 0; bj < 2; ++bj)
; #pragma unroll
;                         for (int n = 0; n < 2; ++n) bsh[m][bj][n] = *(const u32x2*)(anp + (size_t)(ai * HALF + m * 16) * DM + bj * HALF + n * 16);
;             }
; #pragma unroll
;             for (int mp = 0; mp < 2; ++mp) {
;                 if (FROM_F32) {
; #pragma unroll
;                     for (int mm = 0; mm < 2; ++mm)
; #pragma unroll
;                         for (int bj = 0; bj < 2; ++bj)
; #pragma unroll
;                             for (int n = 0; n < 2; ++n) bsf[mm][bj][n] = *(const f32x4*)(basep + (size_t)(ai * HALF + (2 * mp + mm) * 16) * DM + bj * HALF + n * 16);
;                 }
; #pragma unroll
;                 for (int mm = 0; mm < 2; ++mm) {
;                     const int m = 2 * mp + mm; const size_t ro = (size_t)(ai * HALF + m * 16) * DM; float sq = 0.f;
; #pragma unroll
;                     for (int bj = 0; bj < 2; ++bj)
; #pragma unroll
;                         for (int n = 0; n < 2; ++n) {
;                             f32x4 xo;
;                             if (FROM_F32) xo = bsf[mm][bj][n];
;                             else { const u32x2 r_ = bsh[m][bj][n]; xo = (f32x4){bf2f(r_.x & 0xffff), bf2f(r_.x >> 16), bf2f(r_.y & 0xffff), bf2f(r_.y >> 16)} * rgv[bj][n]; }
;                             const f32x4 xn = xo + gvv[bj][n] * acc[ai][bj][m][n];
;                             sq += xn[0] * xn[0] + xn[1] * xn[1] + xn[2] * xn[2] + xn[3] * xn[3];
;                             if (HAS_AN) { const f32x4 hv = xn * gsv[bj][n]; u32x2 o; o.x = pk2(hv[0], hv[1]); o.y = pk2(hv[2], hv[3]); *(u32x2*)(anp + ro + bj * HALF + n * 16) = o; }
;                             else *(f32x4*)(outp + ro + bj * HALF + n * 16) = xn; }
;                     sq = rows_sum(sq);
;                     if (fq == (m & 3)) __hip_atomic_fetch_add(ssqp + ai * HALF + m * 16, sq, __ATOMIC_RELAXED, __HIP_MEMORY_SCOPE_AGENT);
.LBB0_916:
	s_or_b64 exec, exec, s[58:59]
	v_add_co_u32_e32 v136, vcc, 0x40000, v206
	s_nop 1
	v_addc_co_u32_e32 v137, vcc, 0, v207, vcc
	s_waitcnt vmcnt(8)
	v_mov_b32_e32 v142, v158
	v_mov_b32_e32 v143, v159
	v_mov_b32_e32 v144, v160
	v_mov_b32_e32 v145, v161
	v_mov_b32_e32 v140, v162
	v_mov_b32_e32 v141, v163
	v_mov_b32_e32 v138, v164
	v_mov_b32_e32 v139, v165
	v_add_co_u32_e32 v112, vcc, 0x48000, v206
	v_lshlrev_b32_e32 v146, 16, v142
	v_addc_co_u32_e32 v113, vcc, 0, v207, vcc
	v_mov_b32_e32 v134, v166
	v_mov_b32_e32 v135, v167
	v_mov_b32_e32 v132, v168
	v_mov_b32_e32 v133, v169
	v_mov_b32_e32 v130, v170
	v_mov_b32_e32 v131, v171
	v_mov_b32_e32 v128, v172
	v_mov_b32_e32 v129, v173
	v_add_co_u32_e32 v112, vcc, 0x50000, v206
	v_and_b32_e32 v147, 0xffff0000, v142
	s_nop 0
	v_addc_co_u32_e32 v113, vcc, 0, v207, vcc
	v_mov_b32_e32 v126, v174
	v_mov_b32_e32 v127, v175
	v_mov_b32_e32 v124, v224
	v_mov_b32_e32 v125, v225
	v_mov_b32_e32 v122, v228
	v_mov_b32_e32 v123, v229
	v_mov_b32_e32 v120, v232
	v_mov_b32_e32 v121, v233
	v_add_co_u32_e32 v112, vcc, 0x58000, v206
	v_lshlrev_b32_e32 v142, 16, v143
	s_nop 0
	v_addc_co_u32_e32 v113, vcc, 0, v207, vcc
	v_mov_b32_e32 v118, v234
	v_mov_b32_e32 v119, v235
	v_mov_b32_e32 v116, v236
	v_mov_b32_e32 v117, v237
	v_mov_b32_e32 v114, v240
	v_mov_b32_e32 v115, v241
	s_nop 0
	v_mov_b32_e32 v112, v242
	v_mov_b32_e32 v113, v243
	v_and_b32_e32 v143, 0xffff0000, v143
	v_pk_mul_f32 v[146:147], v[108:109], v[146:147]
	v_pk_mul_f32 v[142:143], v[110:111], v[142:143]
	v_pk_fma_f32 v[104:105], v[104:105], v[100:101], v[146:147]
	v_pk_fma_f32 v[106:107], v[106:107], v[102:103], v[142:143]
	v_mul_f32_e32 v142, v105, v105
	v_fmac_f32_e32 v142, v104, v104
	v_fmac_f32_e32 v142, v106, v106
	v_fmac_f32_e32 v142, v107, v107
	v_pk_mul_f32 v[106:107], v[98:99], v[106:107]
	v_pk_mul_f32 v[104:105], v[96:97], v[104:105]
	s_nop 0
	v_cvt_pk_bf16_f32 v104, v104, v105
	v_cvt_pk_bf16_f32 v105, v106, v107
	global_store_dwordx2 v[136:137], v[104:105], off
	s_waitcnt vmcnt(15)
	v_lshlrev_b32_e32 v104, 16, v144
	v_and_b32_e32 v105, 0xffff0000, v144
	v_pk_mul_f32 v[104:105], v[92:93], v[104:105]
	v_lshlrev_b32_e32 v106, 16, v145
	v_and_b32_e32 v107, 0xffff0000, v145
	v_pk_fma_f32 v[56:57], v[56:57], v[88:89], v[104:105]
	v_pk_mul_f32 v[106:107], v[94:95], v[106:107]
	v_mul_f32_e32 v104, v57, v57
	v_pk_fma_f32 v[58:59], v[58:59], v[90:91], v[106:107]
	v_fmac_f32_e32 v104, v56, v56
	v_fmac_f32_e32 v104, v58, v58
	v_fmac_f32_e32 v104, v59, v59
	v_pk_mul_f32 v[58:59], v[86:87], v[58:59]
	v_pk_mul_f32 v[56:57], v[84:85], v[56:57]
	v_add_f32_e32 v104, v142, v104
	v_cvt_pk_bf16_f32 v56, v56, v57
	v_cvt_pk_bf16_f32 v57, v58, v59
	global_store_dwordx2 v[136:137], v[56:57], off offset:32
	s_waitcnt vmcnt(15)
	v_lshlrev_b32_e32 v56, 16, v140
	v_and_b32_e32 v57, 0xffff0000, v140
	v_pk_mul_f32 v[56:57], v[80:81], v[56:57]
	v_lshlrev_b32_e32 v58, 16, v141
	v_and_b32_e32 v59, 0xffff0000, v141
	v_pk_fma_f32 v[52:53], v[52:53], v[76:77], v[56:57]
	v_pk_mul_f32 v[58:59], v[82:83], v[58:59]
	v_mul_f32_e32 v56, v53, v53
	v_pk_fma_f32 v[54:55], v[54:55], v[78:79], v[58:59]
	v_fmac_f32_e32 v56, v52, v52
	v_fmac_f32_e32 v56, v54, v54
	v_fmac_f32_e32 v56, v55, v55
	v_pk_mul_f32 v[54:55], v[74:75], v[54:55]
	v_pk_mul_f32 v[52:53], v[72:73], v[52:53]
	v_add_f32_e32 v56, v104, v56
	v_cvt_pk_bf16_f32 v52, v52, v53
	v_cvt_pk_bf16_f32 v53, v54, v55
	global_store_dwordx2 v[136:137], v[52:53], off offset:256
	s_waitcnt vmcnt(15)
	v_lshlrev_b32_e32 v52, 16, v138
	v_and_b32_e32 v53, 0xffff0000, v138
	v_pk_mul_f32 v[52:53], v[68:69], v[52:53]
	v_lshlrev_b32_e32 v54, 16, v139
	v_and_b32_e32 v55, 0xffff0000, v139
	v_pk_fma_f32 v[48:49], v[48:49], v[64:65], v[52:53]
	v_pk_mul_f32 v[54:55], v[70:71], v[54:55]
	v_mul_f32_e32 v52, v49, v49
	v_pk_fma_f32 v[50:51], v[50:51], v[66:67], v[54:55]
	v_fmac_f32_e32 v52, v48, v48
	v_fmac_f32_e32 v52, v50, v50
	v_fmac_f32_e32 v52, v51, v51
	v_pk_mul_f32 v[50:51], v[62:63], v[50:51]
	v_pk_mul_f32 v[48:49], v[60:61], v[48:49]
	v_add_f32_e32 v52, v56, v52
	v_cvt_pk_bf16_f32 v48, v48, v49
	v_cvt_pk_bf16_f32 v49, v50, v51
	global_store_dwordx2 v[136:137], v[48:49], off offset:288
	v_mov_b32_e32 v48, v52
	s_nop 1
	v_permlane16_swap_b32_e32 v52, v48
	v_add_f32_e32 v48, v52, v48
	v_mov_b32_e32 v49, v48
	s_nop 1
	v_permlane32_swap_b32_e32 v48, v49
	s_and_saveexec_b64 s[58:59], s[8:9]
	s_cbranch_execz .LBB0_918
	v_add_f32_e32 v48, v48, v49
	global_atomic_add_f32 v[204:205], v48, off offset:512

; __device__ __forceinline__ float bf2f(unsigned h) { return __uint_as_float(h << 16); }
; __device__ __forceinline__ unsigned pk2(float lo, float hi) { f32x2 v = {lo, hi}; bf16x2_t b = __builtin_convertvector(v, bf16x2_t); return __builtin_bit_cast(unsigned, b); }
;     __device__ __forceinline__ void operator()(const f32x4 (&acc)[2][2][4][2], const Unit& u, int wr, int wc, int fr, int fq) const {
;     ...
;                 for (int m = 0; m < 4; ++m)
; #pragma unroll
;                     for (int bj = 0; bj < 2; ++bj)
; #pragma unroll
;                         for (int n = 0; n < 2; ++n) bsh[m][bj][n] = *(const u32x2*)(anp + (size_t)(ai * HALF + m * 16) * DM + bj * HALF + n * 16);
;             }
; #pragma unroll
;             for (int mp = 0; mp < 2; ++mp) {
;                 if (FROM_F32) {
; #pragma unroll
;                     for (int mm = 0; mm < 2; ++mm)
; #pragma unroll
;                         for (int bj = 0; bj < 2; ++bj)
; #pragma unroll
;                             for (int n = 0; n < 2; ++n) bsf[mm][bj][n] = *(const f32x4*)(basep + (size_t)(ai * HALF + (2 * mp + mm) * 16) * DM + bj * HALF + n * 16);
;                 }
; #pragma unroll
;                 for (int mm = 0; mm < 2; ++mm) {
;                     const int m = 2 * mp + mm; const size_t ro = (size_t)(ai * HALF + m * 16) * DM; float sq = 0.f;
; #pragma unroll
;                     for (int bj = 0; bj < 2; ++bj)
; #pragma unroll
;                         for (int n = 0; n < 2; ++n) {
;                             f32x4 xo;
;                             if (FROM_F32) xo = bsf[mm][bj][n];
;                             else { const u32x2 r_ = bsh[m][bj][n]; xo = (f32x4){bf2f(r_.x & 0xffff), bf2f(r_.x >> 16), bf2f(r_.y & 0xffff), bf2f(r_.y >> 16)} * rgv[bj][n]; }
;                             const f32x4 xn = xo + gvv[bj][n] * acc[ai][bj][m][n];
;                             sq += xn[0] * xn[0] + xn[1] * xn[1] + xn[2] * xn[2] + xn[3] * xn[3];
;                             if (HAS_AN) { const f32x4 hv = xn * gsv[bj][n]; u32x2 o; o.x = pk2(hv[0], hv[1]); o.y = pk2(hv[2], hv[3]); *(u32x2*)(anp + ro + bj * HALF + n * 16) = o; }
;                             else *(f32x4*)(outp + ro + bj * HALF + n * 16) = xn; }
;                     sq = rows_sum(sq);
;                     if (fq == (m & 3)) __hip_atomic_fetch_add(ssqp + ai * HALF + m * 16, sq, __ATOMIC_RELAXED, __HIP_MEMORY_SCOPE_AGENT);
.LBB0_1098:
	s_or_b64 exec, exec, s[58:59]
	s_mov_b32 s101, 0
	s_mov_b32 s100, 0x40000
	v_lshl_add_u64 v[132:133], v[206:207], 0, s[100:101]
	global_load_dwordx2 v[142:143], v[132:133], off
	global_load_dwordx2 v[144:145], v[132:133], off offset:32
	global_load_dwordx2 v[146:147], v[132:133], off offset:256
	global_load_dwordx2 v[148:149], v[132:133], off offset:288
	s_mov_b32 s100, 0x48000
	v_lshl_add_u64 v[132:133], v[206:207], 0, s[100:101]
	global_load_dwordx2 v[150:151], v[132:133], off
	global_load_dwordx2 v[152:153], v[132:133], off offset:32
	global_load_dwordx2 v[154:155], v[132:133], off offset:256
	global_load_dwordx2 v[156:157], v[132:133], off offset:288
	s_mov_b32 s100, 0x50000
	v_lshl_add_u64 v[132:133], v[206:207], 0, s[100:101]
	global_load_dwordx2 v[158:159], v[132:133], off
	global_load_dwordx2 v[214:215], v[132:133], off offset:32
	global_load_dwordx2 v[218:219], v[132:133], off offset:256
	global_load_dwordx2 v[220:221], v[132:133], off offset:288
	s_mov_b32 s100, 0x58000
	v_lshl_add_u64 v[132:133], v[206:207], 0, s[100:101]
	global_load_dwordx2 v[222:223], v[132:133], off
	global_load_dwordx2 v[224:225], v[132:133], off offset:32
	global_load_dwordx2 v[228:229], v[132:133], off offset:256
	global_load_dwordx2 v[232:233], v[132:133], off offset:288
	s_waitcnt vmcnt(31)
	v_lshlrev_b32_e32 v120, 16, v216
	v_and_b32_e32 v121, 0xffff0000, v216
	v_pk_mul_f32 v[120:121], v[92:93], v[120:121]
	v_lshlrev_b32_e32 v122, 16, v217
	v_and_b32_e32 v123, 0xffff0000, v217
	v_pk_fma_f32 v[108:109], v[108:109], v[204:205], v[120:121]
	v_pk_mul_f32 v[122:123], v[94:95], v[122:123]
	v_mul_f32_e32 v120, v109, v109
	v_pk_fma_f32 v[110:111], v[110:111], v[202:203], v[122:123]
	v_fmac_f32_e32 v120, v108, v108
	v_fmac_f32_e32 v120, v110, v110
	s_mov_b64 s[46:47], 0x18000
	v_fmac_f32_e32 v120, v111, v111
	v_pk_mul_f32 v[110:111], v[78:79], v[110:111]
	v_pk_mul_f32 v[108:109], v[76:77], v[108:109]
	v_lshl_add_u64 v[112:113], v[206:207], 0, s[46:47]
	v_cvt_pk_bf16_f32 v108, v108, v109
	v_cvt_pk_bf16_f32 v109, v110, v111
	global_store_dwordx2 v[112:113], v[108:109], off
	s_waitcnt vmcnt(31)
	v_lshlrev_b32_e32 v108, 16, v212
	v_and_b32_e32 v109, 0xffff0000, v212
	v_pk_mul_f32 v[108:109], v[88:89], v[108:109]
	v_lshlrev_b32_e32 v110, 16, v213
	v_and_b32_e32 v111, 0xffff0000, v213
	v_pk_fma_f32 v[104:105], v[104:105], v[200:201], v[108:109]
	v_pk_mul_f32 v[110:111], v[90:91], v[110:111]
	v_mul_f32_e32 v108, v105, v105
	v_pk_fma_f32 v[106:107], v[106:107], v[198:199], v[110:111]
	v_fmac_f32_e32 v108, v104, v104
	v_fmac_f32_e32 v108, v106, v106
	s_mov_b64 s[46:47], 0x18020
	v_fmac_f32_e32 v108, v107, v107
	v_pk_mul_f32 v[106:107], v[70:71], v[106:107]
	v_pk_mul_f32 v[104:105], v[68:69], v[104:105]
	v_lshl_add_u64 v[114:115], v[206:207], 0, s[46:47]
	v_cvt_pk_bf16_f32 v104, v104, v105
	v_cvt_pk_bf16_f32 v105, v106, v107
	global_store_dwordx2 v[114:115], v[104:105], off
	s_waitcnt vmcnt(31)
	v_lshlrev_b32_e32 v104, 16, v210
	v_and_b32_e32 v105, 0xffff0000, v210
	v_pk_mul_f32 v[104:105], v[80:81], v[104:105]
	v_lshlrev_b32_e32 v106, 16, v211
	v_and_b32_e32 v107, 0xffff0000, v211
	v_pk_fma_f32 v[100:101], v[100:101], v[196:197], v[104:105]
	v_pk_mul_f32 v[106:107], v[82:83], v[106:107]
	v_mul_f32_e32 v104, v101, v101
	v_pk_fma_f32 v[102:103], v[102:103], v[194:195], v[106:107]
	v_fmac_f32_e32 v104, v100, v100
	v_fmac_f32_e32 v104, v102, v102
	s_mov_b64 s[46:47], 0x18100
	v_fmac_f32_e32 v104, v103, v103
	v_pk_mul_f32 v[102:103], v[66:67], v[102:103]
	v_pk_mul_f32 v[100:101], v[64:65], v[100:101]
	v_lshl_add_u64 v[116:117], v[206:207], 0, s[46:47]
	v_cvt_pk_bf16_f32 v100, v100, v101
	v_cvt_pk_bf16_f32 v101, v102, v103
	global_store_dwordx2 v[116:117], v[100:101], off
	s_waitcnt vmcnt(31)
	v_lshlrev_b32_e32 v100, 16, v208
	v_and_b32_e32 v101, 0xffff0000, v208
	v_pk_mul_f32 v[100:101], v[72:73], v[100:101]
	v_lshlrev_b32_e32 v102, 16, v209
	v_and_b32_e32 v103, 0xffff0000, v209
	v_pk_fma_f32 v[96:97], v[96:97], v[174:175], v[100:101]
	v_pk_mul_f32 v[102:103], v[74:75], v[102:103]
	v_mul_f32_e32 v100, v97, v97
	v_pk_fma_f32 v[98:99], v[98:99], v[172:173], v[102:103]
	v_fmac_f32_e32 v100, v96, v96
	v_add_f32_e32 v108, v120, v108
	v_fmac_f32_e32 v100, v98, v98
	s_mov_b64 s[46:47], 0x18120
	v_add_f32_e32 v104, v108, v104
	v_fmac_f32_e32 v100, v99, v99
	v_pk_mul_f32 v[98:99], v[62:63], v[98:99]
	v_pk_mul_f32 v[96:97], v[60:61], v[96:97]
	v_lshl_add_u64 v[118:119], v[206:207], 0, s[46:47]
	v_add_f32_e32 v100, v104, v100
	v_cvt_pk_bf16_f32 v96, v96, v97
	v_cvt_pk_bf16_f32 v97, v98, v99
	global_store_dwordx2 v[118:119], v[96:97], off
	v_mov_b32_e32 v96, v100
	s_nop 1
	v_permlane16_swap_b32_e32 v100, v96
	v_add_f32_e32 v96, v100, v96
	v_mov_b32_e32 v97, v96
	s_nop 1
	v_permlane32_swap_b32_e32 v96, v97
	s_and_saveexec_b64 s[58:59], s[18:19]
	s_cbranch_execz .LBB0_1100
	v_add_f32_e32 v96, v96, v97
	global_atomic_add_f32 v[170:171], v96, off offset:192
; __device__ __forceinline__ float bf2f(unsigned h) { return __uint_as_float(h << 16); }
;     __device__ __forceinline__ void operator()(const f32x4 (&acc)[2][2][4][2], const Unit& u, int wr, int wc, int fr, int fq) const {
;     ...
;             if (!FROM_F32) {
; #pragma unroll
;                 for (int m = 0; m < 4; ++m)
; #pragma unroll
;                     for (int bj = 0; bj < 2; ++bj)
; #pragma unroll
;                         for (int n = 0; n < 2; ++n) bsh[m][bj][n] = *(const u32x2*)(anp + (size_t)(ai * HALF + m * 16) * DM + bj * HALF + n * 16);
;             }
; #pragma unroll
;             for (int mp = 0; mp < 2; ++mp) {
;                 if (FROM_F32) {
; #pragma unroll
;                     for (int mm = 0; mm < 2; ++mm)
; #pragma unroll
;                         for (int bj = 0; bj < 2; ++bj)
; #pragma unroll
;                             for (int n = 0; n < 2; ++n) bsf[mm][bj][n] = *(const f32x4*)(basep + (size_t)(ai * HALF + (2 * mp + mm) * 16) * DM + bj * HALF + n * 16);
;                 }
; #pragma unroll
;                 for (int mm = 0; mm < 2; ++mm) {
;                     const int m = 2 * mp + mm; const size_t ro = (size_t)(ai * HALF + m * 16) * DM; float sq = 0.f;
; #pragma unroll
;                     for (int bj = 0; bj < 2; ++bj)
; #pragma unroll
;                         for (int n = 0; n < 2; ++n) {
;                             f32x4 xo;
;                             if (FROM_F32) xo = bsf[mm][bj][n];
;                             else { const u32x2 r_ = bsh[m][bj][n]; xo = (f32x4){bf2f(r_.x & 0xffff), bf2f(r_.x >> 16), bf2f(r_.y & 0xffff), bf2f(r_.y >> 16)} * rgv[bj][n]; }
;                             const f32x4 xn = xo + gvv[bj][n] * acc[ai][bj][m][n];
;                             sq += xn[0] * xn[0] + xn[1] * xn[1] + xn[2] * xn[2] + xn[3] * xn[3];
;                             if (HAS_AN) { const f32x4 hv = xn * gsv[bj][n]; u32x2 o; o.x = pk2(hv[0], hv[1]); o.y = pk2(hv[2], hv[3]); *(u32x2*)(anp + ro + bj * HALF + n * 16) = o; }
;                             else *(f32x4*)(outp + ro + bj * HALF + n * 16) = xn; }
;                     sq = rows_sum(sq);
;                     if (fq == (m & 3)) __hip_atomic_fetch_add(ssqp + ai * HALF + m * 16, sq, __ATOMIC_RELAXED, __HIP_MEMORY_SCOPE_AGENT);
.LBB0_1100:
	s_or_b64 exec, exec, s[58:59]
	v_add_co_u32_e32 v120, vcc, 0x40000, v206
	s_nop 1
	v_addc_co_u32_e32 v121, vcc, 0, v207, vcc
	s_waitcnt vmcnt(4)
	v_mov_b32_e32 v126, v142
	v_mov_b32_e32 v127, v143
	v_mov_b32_e32 v128, v144
	v_mov_b32_e32 v129, v145
	v_mov_b32_e32 v124, v146
	v_mov_b32_e32 v125, v147
	v_mov_b32_e32 v122, v148
	v_mov_b32_e32 v123, v149
	v_add_co_u32_e32 v96, vcc, 0x48000, v206
	v_lshlrev_b32_e32 v130, 16, v126
	v_addc_co_u32_e32 v97, vcc, 0, v207, vcc
	v_mov_b32_e32 v118, v150
	v_mov_b32_e32 v119, v151
	v_mov_b32_e32 v116, v152
	v_mov_b32_e32 v117, v153
	v_mov_b32_e32 v114, v154
	v_mov_b32_e32 v115, v155
	v_mov_b32_e32 v112, v156
	v_mov_b32_e32 v113, v157
	v_add_co_u32_e32 v96, vcc, 0x50000, v206
	v_and_b32_e32 v131, 0xffff0000, v126
	s_nop 0
	v_addc_co_u32_e32 v97, vcc, 0, v207, vcc
	v_mov_b32_e32 v110, v158
	v_mov_b32_e32 v111, v159
	v_mov_b32_e32 v108, v214
	v_mov_b32_e32 v109, v215
	v_mov_b32_e32 v106, v218
	v_mov_b32_e32 v107, v219
	v_mov_b32_e32 v104, v220
	v_mov_b32_e32 v105, v221
	v_add_co_u32_e32 v96, vcc, 0x58000, v206
	v_lshlrev_b32_e32 v126, 16, v127
	s_nop 0
	v_addc_co_u32_e32 v97, vcc, 0, v207, vcc
	v_mov_b32_e32 v102, v222
	v_mov_b32_e32 v103, v223
	v_mov_b32_e32 v100, v224
	v_mov_b32_e32 v101, v225
	v_mov_b32_e32 v98, v228
	v_mov_b32_e32 v99, v229
	s_nop 0
	v_mov_b32_e32 v96, v232
	v_mov_b32_e32 v97, v233
	v_and_b32_e32 v127, 0xffff0000, v127
	v_pk_mul_f32 v[130:131], v[92:93], v[130:131]
	v_pk_mul_f32 v[126:127], v[94:95], v[126:127]
	v_pk_fma_f32 v[84:85], v[84:85], v[204:205], v[130:131]
	v_pk_fma_f32 v[86:87], v[86:87], v[202:203], v[126:127]
	v_mul_f32_e32 v126, v85, v85
	v_fmac_f32_e32 v126, v84, v84
	v_fmac_f32_e32 v126, v86, v86
	v_fmac_f32_e32 v126, v87, v87
	v_pk_mul_f32 v[86:87], v[78:79], v[86:87]
	v_pk_mul_f32 v[84:85], v[76:77], v[84:85]
	s_nop 0
	v_cvt_pk_bf16_f32 v84, v84, v85
	v_cvt_pk_bf16_f32 v85, v86, v87
	global_store_dwordx2 v[120:121], v[84:85], off
	s_waitcnt vmcnt(15)
	v_lshlrev_b32_e32 v84, 16, v128
	v_and_b32_e32 v85, 0xffff0000, v128
	v_pk_mul_f32 v[84:85], v[88:89], v[84:85]
	v_lshlrev_b32_e32 v86, 16, v129
	v_and_b32_e32 v87, 0xffff0000, v129
	v_pk_fma_f32 v[56:57], v[56:57], v[200:201], v[84:85]
	v_pk_mul_f32 v[86:87], v[90:91], v[86:87]
	v_mul_f32_e32 v84, v57, v57
	v_pk_fma_f32 v[58:59], v[58:59], v[198:199], v[86:87]
	v_fmac_f32_e32 v84, v56, v56
	v_fmac_f32_e32 v84, v58, v58
	v_fmac_f32_e32 v84, v59, v59
	v_pk_mul_f32 v[58:59], v[70:71], v[58:59]
	v_pk_mul_f32 v[56:57], v[68:69], v[56:57]
	v_add_f32_e32 v84, v126, v84
	v_cvt_pk_bf16_f32 v56, v56, v57
	v_cvt_pk_bf16_f32 v57, v58, v59
	global_store_dwordx2 v[120:121], v[56:57], off offset:32
	s_waitcnt vmcnt(15)
	v_lshlrev_b32_e32 v56, 16, v124
	v_and_b32_e32 v57, 0xffff0000, v124
	v_pk_mul_f32 v[56:57], v[80:81], v[56:57]
	v_lshlrev_b32_e32 v58, 16, v125
	v_and_b32_e32 v59, 0xffff0000, v125
	v_pk_fma_f32 v[52:53], v[52:53], v[196:197], v[56:57]
	v_pk_mul_f32 v[58:59], v[82:83], v[58:59]
	v_mul_f32_e32 v56, v53, v53
	v_pk_fma_f32 v[54:55], v[54:55], v[194:195], v[58:59]
	v_fmac_f32_e32 v56, v52, v52
	v_fmac_f32_e32 v56, v54, v54
	v_fmac_f32_e32 v56, v55, v55
	v_pk_mul_f32 v[54:55], v[66:67], v[54:55]
	v_pk_mul_f32 v[52:53], v[64:65], v[52:53]
	v_add_f32_e32 v56, v84, v56
	v_cvt_pk_bf16_f32 v52, v52, v53
	v_cvt_pk_bf16_f32 v53, v54, v55
	global_store_dwordx2 v[120:121], v[52:53], off offset:256
	s_waitcnt vmcnt(15)
	v_lshlrev_b32_e32 v52, 16, v122
	v_and_b32_e32 v53, 0xffff0000, v122
	v_pk_mul_f32 v[52:53], v[72:73], v[52:53]
	v_lshlrev_b32_e32 v54, 16, v123
	v_and_b32_e32 v55, 0xffff0000, v123
	v_pk_fma_f32 v[48:49], v[48:49], v[174:175], v[52:53]
	v_pk_mul_f32 v[54:55], v[74:75], v[54:55]
	v_mul_f32_e32 v52, v49, v49
	v_pk_fma_f32 v[50:51], v[50:51], v[172:173], v[54:55]
	v_fmac_f32_e32 v52, v48, v48
	v_fmac_f32_e32 v52, v50, v50
	v_fmac_f32_e32 v52, v51, v51
	v_pk_mul_f32 v[50:51], v[62:63], v[50:51]
	v_pk_mul_f32 v[48:49], v[60:61], v[48:49]
	v_add_f32_e32 v52, v56, v52
	v_cvt_pk_bf16_f32 v48, v48, v49
	v_cvt_pk_bf16_f32 v49, v50, v51
	global_store_dwordx2 v[120:121], v[48:49], off offset:288
	v_mov_b32_e32 v48, v52
	s_nop 1
	v_permlane16_swap_b32_e32 v52, v48
	v_add_f32_e32 v48, v52, v48
	v_mov_b32_e32 v49, v48
	s_nop 1
	v_permlane32_swap_b32_e32 v48, v49
	s_and_saveexec_b64 s[58:59], s[12:13]
	s_cbranch_execz .LBB0_1102
	v_add_f32_e32 v48, v48, v49
	global_atomic_add_f32 v[170:171], v48, off offset:512

; __device__ __forceinline__ float bf2f(unsigned h) { return __uint_as_float(h << 16); }
; __device__ __forceinline__ unsigned pk2(float lo, float hi) { f32x2 v = {lo, hi}; bf16x2_t b = __builtin_convertvector(v, bf16x2_t); return __builtin_bit_cast(unsigned, b); }
;     __device__ __forceinline__ void operator()(const f32x4 (&acc)[2][2][4][2], const Unit& u, int wr, int wc, int fr, int fq) const {
;     ...
;                 for (int m = 0; m < 4; ++m)
; #pragma unroll
;                     for (int bj = 0; bj < 2; ++bj)
; #pragma unroll
;                         for (int n = 0; n < 2; ++n) bsh[m][bj][n] = *(const u32x2*)(anp + (size_t)(ai * HALF + m * 16) * DM + bj * HALF + n * 16);
;             }
; #pragma unroll
;             for (int mp = 0; mp < 2; ++mp) {
;                 if (FROM_F32) {
; #pragma unroll
;                     for (int mm = 0; mm < 2; ++mm)
; #pragma unroll
;                         for (int bj = 0; bj < 2; ++bj)
; #pragma unroll
;                             for (int n = 0; n < 2; ++n) bsf[mm][bj][n] = *(const f32x4*)(basep + (size_t)(ai * HALF + (2 * mp + mm) * 16) * DM + bj * HALF + n * 16);
;                 }
; #pragma unroll
;                 for (int mm = 0; mm < 2; ++mm) {
;                     const int m = 2 * mp + mm; const size_t ro = (size_t)(ai * HALF + m * 16) * DM; float sq = 0.f;
; #pragma unroll
;                     for (int bj = 0; bj < 2; ++bj)
; #pragma unroll
;                         for (int n = 0; n < 2; ++n) {
;                             f32x4 xo;
;                             if (FROM_F32) xo = bsf[mm][bj][n];
;                             else { const u32x2 r_ = bsh[m][bj][n]; xo = (f32x4){bf2f(r_.x & 0xffff), bf2f(r_.x >> 16), bf2f(r_.y & 0xffff), bf2f(r_.y >> 16)} * rgv[bj][n]; }
;                             const f32x4 xn = xo + gvv[bj][n] * acc[ai][bj][m][n];
;                             sq += xn[0] * xn[0] + xn[1] * xn[1] + xn[2] * xn[2] + xn[3] * xn[3];
;                             if (HAS_AN) { const f32x4 hv = xn * gsv[bj][n]; u32x2 o; o.x = pk2(hv[0], hv[1]); o.y = pk2(hv[2], hv[3]); *(u32x2*)(anp + ro + bj * HALF + n * 16) = o; }
;                             else *(f32x4*)(outp + ro + bj * HALF + n * 16) = xn; }
;                     sq = rows_sum(sq);
;                     if (fq == (m & 3)) __hip_atomic_fetch_add(ssqp + ai * HALF + m * 16, sq, __ATOMIC_RELAXED, __HIP_MEMORY_SCOPE_AGENT);
.LBB0_1637:
	s_or_b64 exec, exec, s[58:59]
	s_mov_b32 s101, 0
	s_mov_b32 s100, 0x40000
	v_lshl_add_u64 v[156:157], v[196:197], 0, s[100:101]
	global_load_dwordx2 v[158:159], v[156:157], off
	global_load_dwordx2 v[160:161], v[156:157], off offset:32
	global_load_dwordx2 v[162:163], v[156:157], off offset:256
	global_load_dwordx2 v[164:165], v[156:157], off offset:288
	s_mov_b32 s100, 0x48000
	v_lshl_add_u64 v[156:157], v[196:197], 0, s[100:101]
	global_load_dwordx2 v[166:167], v[156:157], off
	global_load_dwordx2 v[168:169], v[156:157], off offset:32
	global_load_dwordx2 v[170:171], v[156:157], off offset:256
	global_load_dwordx2 v[172:173], v[156:157], off offset:288
	s_mov_b32 s100, 0x50000
	v_lshl_add_u64 v[156:157], v[196:197], 0, s[100:101]
	global_load_dwordx2 v[174:175], v[156:157], off
	global_load_dwordx2 v[216:217], v[156:157], off offset:32
	global_load_dwordx2 v[218:219], v[156:157], off offset:256
	global_load_dwordx2 v[220:221], v[156:157], off offset:288
	s_mov_b32 s100, 0x58000
	v_lshl_add_u64 v[156:157], v[196:197], 0, s[100:101]
	global_load_dwordx2 v[222:223], v[156:157], off
	global_load_dwordx2 v[224:225], v[156:157], off offset:32
	global_load_dwordx2 v[236:237], v[156:157], off offset:256
	global_load_dwordx2 v[240:241], v[156:157], off offset:288
	v_lshlrev_b32_e32 v152, 16, v214
	v_and_b32_e32 v153, 0xffff0000, v214
	v_pk_mul_f32 v[152:153], v[96:97], v[152:153]
	v_lshlrev_b32_e32 v154, 16, v215
	v_and_b32_e32 v155, 0xffff0000, v215
	v_pk_fma_f32 v[140:141], v[140:141], v[92:93], v[152:153]
	v_pk_mul_f32 v[154:155], v[98:99], v[154:155]
	v_mul_f32_e32 v152, v141, v141
	v_pk_fma_f32 v[142:143], v[142:143], v[94:95], v[154:155]
	v_fmac_f32_e32 v152, v140, v140
	v_fmac_f32_e32 v152, v142, v142
	s_mov_b64 s[46:47], 0x10000
	v_fmac_f32_e32 v152, v143, v143
	v_pk_mul_f32 v[142:143], v[86:87], v[142:143]
	v_pk_mul_f32 v[140:141], v[84:85], v[140:141]
	v_lshl_add_u64 v[144:145], v[196:197], 0, s[46:47]
	v_cvt_pk_bf16_f32 v140, v140, v141
	v_cvt_pk_bf16_f32 v141, v142, v143
	global_store_dwordx2 v[144:145], v[140:141], off
	v_lshlrev_b32_e32 v140, 16, v212
	v_and_b32_e32 v141, 0xffff0000, v212
	v_pk_mul_f32 v[140:141], v[80:81], v[140:141]
	v_lshlrev_b32_e32 v142, 16, v213
	v_and_b32_e32 v143, 0xffff0000, v213
	v_pk_fma_f32 v[136:137], v[136:137], v[76:77], v[140:141]
	v_pk_mul_f32 v[142:143], v[82:83], v[142:143]
	v_mul_f32_e32 v140, v137, v137
	v_pk_fma_f32 v[138:139], v[138:139], v[78:79], v[142:143]
	v_fmac_f32_e32 v140, v136, v136
	v_fmac_f32_e32 v140, v138, v138
	s_mov_b64 s[46:47], 0x10020
	v_fmac_f32_e32 v140, v139, v139
	v_pk_mul_f32 v[138:139], v[74:75], v[138:139]
	v_pk_mul_f32 v[136:137], v[72:73], v[136:137]
	v_lshl_add_u64 v[146:147], v[196:197], 0, s[46:47]
	v_cvt_pk_bf16_f32 v136, v136, v137
	v_cvt_pk_bf16_f32 v137, v138, v139
	global_store_dwordx2 v[146:147], v[136:137], off
	v_lshlrev_b32_e32 v136, 16, v210
	v_and_b32_e32 v137, 0xffff0000, v210
	v_pk_mul_f32 v[136:137], v[68:69], v[136:137]
	v_lshlrev_b32_e32 v138, 16, v211
	v_and_b32_e32 v139, 0xffff0000, v211
	v_pk_fma_f32 v[132:133], v[132:133], v[64:65], v[136:137]
	v_pk_mul_f32 v[138:139], v[70:71], v[138:139]
	v_mul_f32_e32 v136, v133, v133
	v_pk_fma_f32 v[134:135], v[134:135], v[66:67], v[138:139]
	v_fmac_f32_e32 v136, v132, v132
	v_fmac_f32_e32 v136, v134, v134
	s_mov_b64 s[46:47], 0x10100
	v_fmac_f32_e32 v136, v135, v135
	v_pk_mul_f32 v[134:135], v[102:103], v[134:135]
	v_pk_mul_f32 v[132:133], v[100:101], v[132:133]
	v_lshl_add_u64 v[148:149], v[196:197], 0, s[46:47]
	v_cvt_pk_bf16_f32 v132, v132, v133
	v_cvt_pk_bf16_f32 v133, v134, v135
	global_store_dwordx2 v[148:149], v[132:133], off
	v_lshlrev_b32_e32 v132, 16, v208
	v_and_b32_e32 v133, 0xffff0000, v208
	v_pk_mul_f32 v[132:133], v[108:109], v[132:133]
	v_lshlrev_b32_e32 v134, 16, v209
	v_and_b32_e32 v135, 0xffff0000, v209
	v_pk_fma_f32 v[128:129], v[128:129], v[104:105], v[132:133]
	v_pk_mul_f32 v[134:135], v[110:111], v[134:135]
	v_mul_f32_e32 v132, v129, v129
	v_pk_fma_f32 v[130:131], v[130:131], v[106:107], v[134:135]
	v_fmac_f32_e32 v132, v128, v128
	v_add_f32_e32 v140, v152, v140
	v_fmac_f32_e32 v132, v130, v130
	s_mov_b64 s[46:47], 0x10120
	v_add_f32_e32 v136, v140, v136
	v_fmac_f32_e32 v132, v131, v131
	v_pk_mul_f32 v[130:131], v[90:91], v[130:131]
	v_pk_mul_f32 v[128:129], v[88:89], v[128:129]
	v_lshl_add_u64 v[150:151], v[196:197], 0, s[46:47]
	v_add_f32_e32 v132, v136, v132
	v_cvt_pk_bf16_f32 v128, v128, v129
	v_cvt_pk_bf16_f32 v129, v130, v131
	global_store_dwordx2 v[150:151], v[128:129], off
	v_mov_b32_e32 v128, v132
	s_nop 1
	v_permlane16_swap_b32_e32 v132, v128
	v_add_f32_e32 v128, v132, v128
	v_mov_b32_e32 v129, v128
	s_nop 1
	v_permlane32_swap_b32_e32 v128, v129
	s_and_saveexec_b64 s[58:59], s[16:17]
	v_readlane_b32 s80, v255, 2
	v_readlane_b32 s81, v255, 3
	s_cbranch_execz .LBB0_1639
	v_add_f32_e32 v128, v128, v129
	global_atomic_add_f32 v[198:199], v128, off offset:128

; __device__ __forceinline__ float bf2f(unsigned h) { return __uint_as_float(h << 16); }
;     __device__ __forceinline__ void operator()(const f32x4 (&acc)[2][2][4][2], const Unit& u, int wr, int wc, int fr, int fq) const {
;     ...
;             if (!FROM_F32) {
; #pragma unroll
;                 for (int m = 0; m < 4; ++m)
; #pragma unroll
;                     for (int bj = 0; bj < 2; ++bj)
; #pragma unroll
;                         for (int n = 0; n < 2; ++n) bsh[m][bj][n] = *(const u32x2*)(anp + (size_t)(ai * HALF + m * 16) * DM + bj * HALF + n * 16);
;             }
; #pragma unroll
;             for (int mp = 0; mp < 2; ++mp) {
;                 if (FROM_F32) {
; #pragma unroll
;                     for (int mm = 0; mm < 2; ++mm)
; #pragma unroll
;                         for (int bj = 0; bj < 2; ++bj)
; #pragma unroll
;                             for (int n = 0; n < 2; ++n) bsf[mm][bj][n] = *(const f32x4*)(basep + (size_t)(ai * HALF + (2 * mp + mm) * 16) * DM + bj * HALF + n * 16);
;                 }
; #pragma unroll
;                 for (int mm = 0; mm < 2; ++mm) {
;                     const int m = 2 * mp + mm; const size_t ro = (size_t)(ai * HALF + m * 16) * DM; float sq = 0.f;
; #pragma unroll
;                     for (int bj = 0; bj < 2; ++bj)
; #pragma unroll
;                         for (int n = 0; n < 2; ++n) {
;                             f32x4 xo;
;                             if (FROM_F32) xo = bsf[mm][bj][n];
;                             else { const u32x2 r_ = bsh[m][bj][n]; xo = (f32x4){bf2f(r_.x & 0xffff), bf2f(r_.x >> 16), bf2f(r_.y & 0xffff), bf2f(r_.y >> 16)} * rgv[bj][n]; }
;                             const f32x4 xn = xo + gvv[bj][n] * acc[ai][bj][m][n];
;                             sq += xn[0] * xn[0] + xn[1] * xn[1] + xn[2] * xn[2] + xn[3] * xn[3];
;                             if (HAS_AN) { const f32x4 hv = xn * gsv[bj][n]; u32x2 o; o.x = pk2(hv[0], hv[1]); o.y = pk2(hv[2], hv[3]); *(u32x2*)(anp + ro + bj * HALF + n * 16) = o; }
;                             else *(f32x4*)(outp + ro + bj * HALF + n * 16) = xn; }
;                     sq = rows_sum(sq);
;                     if (fq == (m & 3)) __hip_atomic_fetch_add(ssqp + ai * HALF + m * 16, sq, __ATOMIC_RELAXED, __HIP_MEMORY_SCOPE_AGENT);
.LBB0_1641:
	s_or_b64 exec, exec, s[58:59]
	v_add_co_u32_e32 v134, vcc, 0x40000, v196
	s_nop 1
	v_addc_co_u32_e32 v135, vcc, 0, v197, vcc
	s_waitcnt vmcnt(8)
	v_mov_b32_e32 v140, v158
	v_mov_b32_e32 v141, v159
	v_mov_b32_e32 v142, v160
	v_mov_b32_e32 v143, v161
	v_mov_b32_e32 v144, v162
	v_mov_b32_e32 v145, v163
	v_mov_b32_e32 v138, v164
	v_mov_b32_e32 v139, v165
	v_add_co_u32_e32 v112, vcc, 0x48000, v196
	v_lshlrev_b32_e32 v146, 16, v140
	v_addc_co_u32_e32 v113, vcc, 0, v197, vcc
	v_add_co_u32_e32 v114, vcc, 0x50000, v196
	v_mov_b32_e32 v136, v166
	v_mov_b32_e32 v137, v167
	v_mov_b32_e32 v132, v168
	v_mov_b32_e32 v133, v169
	v_mov_b32_e32 v130, v170
	v_mov_b32_e32 v131, v171
	v_mov_b32_e32 v128, v172
	v_mov_b32_e32 v129, v173
	v_addc_co_u32_e32 v115, vcc, 0, v197, vcc
	v_add_co_u32_e32 v112, vcc, 0x58000, v196
	v_mov_b32_e32 v126, v174
	v_mov_b32_e32 v127, v175
	v_mov_b32_e32 v124, v216
	v_mov_b32_e32 v125, v217
	v_mov_b32_e32 v122, v218
	v_mov_b32_e32 v123, v219
	v_mov_b32_e32 v120, v220
	v_mov_b32_e32 v121, v221
	v_addc_co_u32_e32 v113, vcc, 0, v197, vcc
	v_mov_b32_e32 v118, v222
	v_mov_b32_e32 v119, v223
	v_mov_b32_e32 v116, v224
	v_mov_b32_e32 v117, v225
	v_mov_b32_e32 v114, v236
	v_mov_b32_e32 v115, v237
	s_nop 0
	v_mov_b32_e32 v112, v240
	v_mov_b32_e32 v113, v241
	v_and_b32_e32 v147, 0xffff0000, v140
	s_waitcnt vmcnt(14)
	v_lshlrev_b32_e32 v148, 16, v142
	v_and_b32_e32 v149, 0xffff0000, v142
	s_waitcnt vmcnt(13)
	v_lshlrev_b32_e32 v150, 16, v144
	v_and_b32_e32 v151, 0xffff0000, v144
	v_pk_mul_f32 v[146:147], v[96:97], v[146:147]
	v_pk_mul_f32 v[148:149], v[80:81], v[148:149]
	v_lshlrev_b32_e32 v140, 16, v141
	v_and_b32_e32 v141, 0xffff0000, v141
	v_lshlrev_b32_e32 v142, 16, v143
	v_and_b32_e32 v143, 0xffff0000, v143
	v_lshlrev_b32_e32 v144, 16, v145
	v_and_b32_e32 v145, 0xffff0000, v145
	v_pk_mul_f32 v[150:151], v[68:69], v[150:151]
	v_pk_fma_f32 v[60:61], v[60:61], v[92:93], v[146:147]
	v_pk_fma_f32 v[56:57], v[56:57], v[76:77], v[148:149]
	s_waitcnt vmcnt(12)
	v_lshlrev_b32_e32 v152, 16, v138
	v_and_b32_e32 v153, 0xffff0000, v138
	v_pk_mul_f32 v[140:141], v[98:99], v[140:141]
	v_pk_mul_f32 v[142:143], v[82:83], v[142:143]
	v_pk_mul_f32 v[144:145], v[70:71], v[144:145]
	v_pk_fma_f32 v[52:53], v[52:53], v[64:65], v[150:151]
	v_mul_f32_e32 v138, v61, v61
	v_mul_f32_e32 v154, v57, v57
	v_pk_fma_f32 v[62:63], v[62:63], v[94:95], v[140:141]
	v_pk_fma_f32 v[58:59], v[58:59], v[78:79], v[142:143]
	v_pk_fma_f32 v[54:55], v[54:55], v[66:67], v[144:145]
	v_mul_f32_e32 v155, v53, v53
	v_fmac_f32_e32 v138, v60, v60
	v_fmac_f32_e32 v154, v56, v56
	v_pk_mul_f32 v[148:149], v[102:103], v[54:55]
	v_pk_mul_f32 v[150:151], v[100:101], v[52:53]
	v_fmac_f32_e32 v155, v52, v52
	v_fmac_f32_e32 v138, v62, v62
	v_fmac_f32_e32 v154, v58, v58
	v_pk_mul_f32 v[144:145], v[74:75], v[58:59]
	v_pk_mul_f32 v[146:147], v[72:73], v[56:57]
	v_cvt_pk_bf16_f32 v52, v150, v151
	v_cvt_pk_bf16_f32 v53, v148, v149
	v_fmac_f32_e32 v155, v54, v54
	v_fmac_f32_e32 v138, v63, v63
	v_fmac_f32_e32 v154, v59, v59
	v_cvt_pk_bf16_f32 v56, v146, v147
	v_cvt_pk_bf16_f32 v57, v144, v145
	global_store_dwordx2 v[134:135], v[52:53], off offset:256
	v_fmac_f32_e32 v155, v55, v55
	v_add_f32_e32 v52, v138, v154
	global_store_dwordx2 v[134:135], v[56:57], off offset:32
	v_add_f32_e32 v56, v52, v155
	v_lshlrev_b32_e32 v52, 16, v139
	v_and_b32_e32 v53, 0xffff0000, v139
	v_pk_mul_f32 v[54:55], v[108:109], v[152:153]
	v_pk_mul_f32 v[52:53], v[110:111], v[52:53]
	v_pk_fma_f32 v[48:49], v[48:49], v[104:105], v[54:55]
	v_pk_fma_f32 v[50:51], v[50:51], v[106:107], v[52:53]
	v_mul_f32_e32 v52, v49, v49
	v_fmac_f32_e32 v52, v48, v48
	v_fmac_f32_e32 v52, v50, v50
	v_fmac_f32_e32 v52, v51, v51
	v_pk_mul_f32 v[50:51], v[90:91], v[50:51]
	v_pk_mul_f32 v[48:49], v[88:89], v[48:49]
	v_add_f32_e32 v52, v56, v52
	v_cvt_pk_bf16_f32 v48, v48, v49
	v_cvt_pk_bf16_f32 v49, v50, v51
	global_store_dwordx2 v[134:135], v[48:49], off offset:288
	v_mov_b32_e32 v48, v52
	s_nop 1
	v_permlane16_swap_b32_e32 v52, v48
	v_add_f32_e32 v48, v52, v48
	v_pk_mul_f32 v[140:141], v[86:87], v[62:63]
	v_pk_mul_f32 v[142:143], v[84:85], v[60:61]
	v_mov_b32_e32 v49, v48
	v_cvt_pk_bf16_f32 v60, v142, v143
	v_cvt_pk_bf16_f32 v61, v140, v141
	v_permlane32_swap_b32_e32 v48, v49
	global_store_dwordx2 v[134:135], v[60:61], off
	s_and_saveexec_b64 s[58:59], s[12:13]
	s_cbranch_execz .LBB0_1643
	v_add_f32_e32 v48, v48, v49
	global_atomic_add_f32 v[198:199], v48, off offset:512

; __device__ __forceinline__ float bf2f(unsigned h) { return __uint_as_float(h << 16); }
; __device__ __forceinline__ unsigned pk2(float lo, float hi) { f32x2 v = {lo, hi}; bf16x2_t b = __builtin_convertvector(v, bf16x2_t); return __builtin_bit_cast(unsigned, b); }
;     __device__ __forceinline__ void operator()(const f32x4 (&acc)[2][2][4][2], const Unit& u, int wr, int wc, int fr, int fq) const {
;     ...
;                 for (int m = 0; m < 4; ++m)
; #pragma unroll
;                     for (int bj = 0; bj < 2; ++bj)
; #pragma unroll
;                         for (int n = 0; n < 2; ++n) bsh[m][bj][n] = *(const u32x2*)(anp + (size_t)(ai * HALF + m * 16) * DM + bj * HALF + n * 16);
;             }
; #pragma unroll
;             for (int mp = 0; mp < 2; ++mp) {
;                 if (FROM_F32) {
; #pragma unroll
;                     for (int mm = 0; mm < 2; ++mm)
; #pragma unroll
;                         for (int bj = 0; bj < 2; ++bj)
; #pragma unroll
;                             for (int n = 0; n < 2; ++n) bsf[mm][bj][n] = *(const f32x4*)(basep + (size_t)(ai * HALF + (2 * mp + mm) * 16) * DM + bj * HALF + n * 16);
;                 }
; #pragma unroll
;                 for (int mm = 0; mm < 2; ++mm) {
;                     const int m = 2 * mp + mm; const size_t ro = (size_t)(ai * HALF + m * 16) * DM; float sq = 0.f;
; #pragma unroll
;                     for (int bj = 0; bj < 2; ++bj)
; #pragma unroll
;                         for (int n = 0; n < 2; ++n) {
;                             f32x4 xo;
;                             if (FROM_F32) xo = bsf[mm][bj][n];
;                             else { const u32x2 r_ = bsh[m][bj][n]; xo = (f32x4){bf2f(r_.x & 0xffff), bf2f(r_.x >> 16), bf2f(r_.y & 0xffff), bf2f(r_.y >> 16)} * rgv[bj][n]; }
;                             const f32x4 xn = xo + gvv[bj][n] * acc[ai][bj][m][n];
;                             sq += xn[0] * xn[0] + xn[1] * xn[1] + xn[2] * xn[2] + xn[3] * xn[3];
;                             if (HAS_AN) { const f32x4 hv = xn * gsv[bj][n]; u32x2 o; o.x = pk2(hv[0], hv[1]); o.y = pk2(hv[2], hv[3]); *(u32x2*)(anp + ro + bj * HALF + n * 16) = o; }
;                             else *(f32x4*)(outp + ro + bj * HALF + n * 16) = xn; }
;                     sq = rows_sum(sq);
;                     if (fq == (m & 3)) __hip_atomic_fetch_add(ssqp + ai * HALF + m * 16, sq, __ATOMIC_RELAXED, __HIP_MEMORY_SCOPE_AGENT);
.LBB0_1821:
	s_or_b64 exec, exec, s[58:59]
	s_mov_b32 s101, 0
	s_mov_b32 s100, 0x40000
	v_lshl_add_u64 v[140:141], v[178:179], 0, s[100:101]
	global_load_dwordx2 v[142:143], v[140:141], off
	global_load_dwordx2 v[144:145], v[140:141], off offset:32
	global_load_dwordx2 v[146:147], v[140:141], off offset:256
	global_load_dwordx2 v[148:149], v[140:141], off offset:288
	s_mov_b32 s100, 0x48000
	v_lshl_add_u64 v[140:141], v[178:179], 0, s[100:101]
	global_load_dwordx2 v[150:151], v[140:141], off
	global_load_dwordx2 v[152:153], v[140:141], off offset:32
	global_load_dwordx2 v[154:155], v[140:141], off offset:256
	global_load_dwordx2 v[156:157], v[140:141], off offset:288
	s_mov_b32 s100, 0x50000
	v_lshl_add_u64 v[140:141], v[178:179], 0, s[100:101]
	global_load_dwordx2 v[158:159], v[140:141], off
	global_load_dwordx2 v[214:215], v[140:141], off offset:32
	global_load_dwordx2 v[216:217], v[140:141], off offset:256
	global_load_dwordx2 v[218:219], v[140:141], off offset:288
	s_mov_b32 s100, 0x58000
	v_lshl_add_u64 v[140:141], v[178:179], 0, s[100:101]
	global_load_dwordx2 v[220:221], v[140:141], off
	global_load_dwordx2 v[222:223], v[140:141], off offset:32
	global_load_dwordx2 v[224:225], v[140:141], off offset:256
	global_load_dwordx2 v[232:233], v[140:141], off offset:288
	v_lshlrev_b32_e32 v136, 16, v212
	v_and_b32_e32 v137, 0xffff0000, v212
	v_pk_mul_f32 v[136:137], v[92:93], v[136:137]
	v_lshlrev_b32_e32 v138, 16, v213
	v_and_b32_e32 v139, 0xffff0000, v213
	v_pk_fma_f32 v[124:125], v[124:125], v[196:197], v[136:137]
	v_pk_mul_f32 v[138:139], v[94:95], v[138:139]
	v_mul_f32_e32 v136, v125, v125
	v_pk_fma_f32 v[126:127], v[126:127], v[194:195], v[138:139]
	v_fmac_f32_e32 v136, v124, v124
	v_fmac_f32_e32 v136, v126, v126
	s_mov_b64 s[58:59], 0x10000
	v_fmac_f32_e32 v136, v127, v127
	v_pk_mul_f32 v[126:127], v[86:87], v[126:127]
	v_pk_mul_f32 v[124:125], v[84:85], v[124:125]
	v_lshl_add_u64 v[128:129], v[178:179], 0, s[58:59]
	v_cvt_pk_bf16_f32 v124, v124, v125
	v_cvt_pk_bf16_f32 v125, v126, v127
	global_store_dwordx2 v[128:129], v[124:125], off
	v_lshlrev_b32_e32 v124, 16, v210
	v_and_b32_e32 v125, 0xffff0000, v210
	v_pk_mul_f32 v[124:125], v[72:73], v[124:125]
	v_lshlrev_b32_e32 v126, 16, v211
	v_and_b32_e32 v127, 0xffff0000, v211
	v_pk_fma_f32 v[120:121], v[120:121], v[192:193], v[124:125]
	v_pk_mul_f32 v[126:127], v[74:75], v[126:127]
	v_mul_f32_e32 v124, v121, v121
	v_pk_fma_f32 v[122:123], v[122:123], v[190:191], v[126:127]
	v_fmac_f32_e32 v124, v120, v120
	v_fmac_f32_e32 v124, v122, v122
	s_mov_b64 s[58:59], 0x10020
	v_fmac_f32_e32 v124, v123, v123
	v_pk_mul_f32 v[122:123], v[66:67], v[122:123]
	v_pk_mul_f32 v[120:121], v[64:65], v[120:121]
	v_lshl_add_u64 v[130:131], v[178:179], 0, s[58:59]
	v_cvt_pk_bf16_f32 v120, v120, v121
	v_cvt_pk_bf16_f32 v121, v122, v123
	global_store_dwordx2 v[130:131], v[120:121], off
	v_lshlrev_b32_e32 v120, 16, v208
	v_and_b32_e32 v121, 0xffff0000, v208
	v_pk_mul_f32 v[120:121], v[76:77], v[120:121]
	v_lshlrev_b32_e32 v122, 16, v209
	v_and_b32_e32 v123, 0xffff0000, v209
	v_pk_fma_f32 v[116:117], v[116:117], v[188:189], v[120:121]
	v_pk_mul_f32 v[122:123], v[78:79], v[122:123]
	v_mul_f32_e32 v120, v117, v117
	v_pk_fma_f32 v[118:119], v[118:119], v[186:187], v[122:123]
	v_fmac_f32_e32 v120, v116, v116
	v_fmac_f32_e32 v120, v118, v118
	s_mov_b64 s[58:59], 0x10100
	v_fmac_f32_e32 v120, v119, v119
	v_pk_mul_f32 v[118:119], v[90:91], v[118:119]
	v_pk_mul_f32 v[116:117], v[88:89], v[116:117]
	v_lshl_add_u64 v[132:133], v[178:179], 0, s[58:59]
	v_cvt_pk_bf16_f32 v116, v116, v117
	v_cvt_pk_bf16_f32 v117, v118, v119
	global_store_dwordx2 v[132:133], v[116:117], off
	v_lshlrev_b32_e32 v116, 16, v206
	v_and_b32_e32 v117, 0xffff0000, v206
	v_pk_mul_f32 v[116:117], v[80:81], v[116:117]
	v_lshlrev_b32_e32 v118, 16, v207
	v_and_b32_e32 v119, 0xffff0000, v207
	v_pk_fma_f32 v[112:113], v[112:113], v[184:185], v[116:117]
	v_pk_mul_f32 v[118:119], v[82:83], v[118:119]
	v_mul_f32_e32 v116, v113, v113
	v_pk_fma_f32 v[114:115], v[114:115], v[182:183], v[118:119]
	v_fmac_f32_e32 v116, v112, v112
	v_add_f32_e32 v124, v136, v124
	v_fmac_f32_e32 v116, v114, v114
	s_mov_b64 s[58:59], 0x10120
	v_add_f32_e32 v120, v124, v120
	v_fmac_f32_e32 v116, v115, v115
	v_pk_mul_f32 v[114:115], v[70:71], v[114:115]
	v_pk_mul_f32 v[112:113], v[68:69], v[112:113]
	v_lshl_add_u64 v[134:135], v[178:179], 0, s[58:59]
	v_add_f32_e32 v116, v120, v116
	v_cvt_pk_bf16_f32 v112, v112, v113
	v_cvt_pk_bf16_f32 v113, v114, v115
	global_store_dwordx2 v[134:135], v[112:113], off
	v_mov_b32_e32 v112, v116
	s_nop 1
	v_permlane16_swap_b32_e32 v116, v112
	v_add_f32_e32 v112, v116, v112
	v_mov_b32_e32 v113, v112
	s_nop 1
	v_permlane32_swap_b32_e32 v112, v113
	s_and_saveexec_b64 s[58:59], s[8:9]
	s_cbranch_execz .LBB0_1823
	v_add_f32_e32 v112, v112, v113
	global_atomic_add_f32 v[174:175], v112, off offset:128

; __device__ __forceinline__ float bf2f(unsigned h) { return __uint_as_float(h << 16); }
;     __device__ __forceinline__ void operator()(const f32x4 (&acc)[2][2][4][2], const Unit& u, int wr, int wc, int fr, int fq) const {
;     ...
;             if (!FROM_F32) {
; #pragma unroll
;                 for (int m = 0; m < 4; ++m)
; #pragma unroll
;                     for (int bj = 0; bj < 2; ++bj)
; #pragma unroll
;                         for (int n = 0; n < 2; ++n) bsh[m][bj][n] = *(const u32x2*)(anp + (size_t)(ai * HALF + m * 16) * DM + bj * HALF + n * 16);
;             }
; #pragma unroll
;             for (int mp = 0; mp < 2; ++mp) {
;                 if (FROM_F32) {
; #pragma unroll
;                     for (int mm = 0; mm < 2; ++mm)
; #pragma unroll
;                         for (int bj = 0; bj < 2; ++bj)
; #pragma unroll
;                             for (int n = 0; n < 2; ++n) bsf[mm][bj][n] = *(const f32x4*)(basep + (size_t)(ai * HALF + (2 * mp + mm) * 16) * DM + bj * HALF + n * 16);
;                 }
; #pragma unroll
;                 for (int mm = 0; mm < 2; ++mm) {
;                     const int m = 2 * mp + mm; const size_t ro = (size_t)(ai * HALF + m * 16) * DM; float sq = 0.f;
; #pragma unroll
;                     for (int bj = 0; bj < 2; ++bj)
; #pragma unroll
;                         for (int n = 0; n < 2; ++n) {
;                             f32x4 xo;
;                             if (FROM_F32) xo = bsf[mm][bj][n];
;                             else { const u32x2 r_ = bsh[m][bj][n]; xo = (f32x4){bf2f(r_.x & 0xffff), bf2f(r_.x >> 16), bf2f(r_.y & 0xffff), bf2f(r_.y >> 16)} * rgv[bj][n]; }
;                             const f32x4 xn = xo + gvv[bj][n] * acc[ai][bj][m][n];
;                             sq += xn[0] * xn[0] + xn[1] * xn[1] + xn[2] * xn[2] + xn[3] * xn[3];
;                             if (HAS_AN) { const f32x4 hv = xn * gsv[bj][n]; u32x2 o; o.x = pk2(hv[0], hv[1]); o.y = pk2(hv[2], hv[3]); *(u32x2*)(anp + ro + bj * HALF + n * 16) = o; }
;                             else *(f32x4*)(outp + ro + bj * HALF + n * 16) = xn; }
;                     sq = rows_sum(sq);
;                     if (fq == (m & 3)) __hip_atomic_fetch_add(ssqp + ai * HALF + m * 16, sq, __ATOMIC_RELAXED, __HIP_MEMORY_SCOPE_AGENT);
.LBB0_1825:
	s_or_b64 exec, exec, s[58:59]
	v_add_co_u32_e32 v118, vcc, 0x40000, v178
	s_nop 1
	v_addc_co_u32_e32 v119, vcc, 0, v179, vcc
	s_waitcnt vmcnt(8)
	v_mov_b32_e32 v124, v142
	v_mov_b32_e32 v125, v143
	v_mov_b32_e32 v126, v144
	v_mov_b32_e32 v127, v145
	v_mov_b32_e32 v128, v146
	v_mov_b32_e32 v129, v147
	v_mov_b32_e32 v122, v148
	v_mov_b32_e32 v123, v149
	v_add_co_u32_e32 v96, vcc, 0x48000, v178
	v_lshlrev_b32_e32 v130, 16, v124
	v_addc_co_u32_e32 v97, vcc, 0, v179, vcc
	v_add_co_u32_e32 v98, vcc, 0x50000, v178
	v_mov_b32_e32 v120, v150
	v_mov_b32_e32 v121, v151
	v_mov_b32_e32 v116, v152
	v_mov_b32_e32 v117, v153
	v_mov_b32_e32 v114, v154
	v_mov_b32_e32 v115, v155
	v_mov_b32_e32 v112, v156
	v_mov_b32_e32 v113, v157
	v_addc_co_u32_e32 v99, vcc, 0, v179, vcc
	v_add_co_u32_e32 v96, vcc, 0x58000, v178
	v_mov_b32_e32 v110, v158
	v_mov_b32_e32 v111, v159
	v_mov_b32_e32 v108, v214
	v_mov_b32_e32 v109, v215
	v_mov_b32_e32 v106, v216
	v_mov_b32_e32 v107, v217
	v_mov_b32_e32 v104, v218
	v_mov_b32_e32 v105, v219
	v_addc_co_u32_e32 v97, vcc, 0, v179, vcc
	v_mov_b32_e32 v102, v220
	v_mov_b32_e32 v103, v221
	v_mov_b32_e32 v100, v222
	v_mov_b32_e32 v101, v223
	v_mov_b32_e32 v98, v224
	v_mov_b32_e32 v99, v225
	s_nop 0
	v_mov_b32_e32 v96, v232
	v_mov_b32_e32 v97, v233
	v_and_b32_e32 v131, 0xffff0000, v124
	s_waitcnt vmcnt(14)
	v_lshlrev_b32_e32 v132, 16, v126
	v_and_b32_e32 v133, 0xffff0000, v126
	s_waitcnt vmcnt(13)
	v_lshlrev_b32_e32 v134, 16, v128
	v_and_b32_e32 v135, 0xffff0000, v128
	v_pk_mul_f32 v[130:131], v[92:93], v[130:131]
	v_pk_mul_f32 v[132:133], v[72:73], v[132:133]
	v_lshlrev_b32_e32 v124, 16, v125
	v_and_b32_e32 v125, 0xffff0000, v125
	v_lshlrev_b32_e32 v126, 16, v127
	v_and_b32_e32 v127, 0xffff0000, v127
	v_lshlrev_b32_e32 v128, 16, v129
	v_and_b32_e32 v129, 0xffff0000, v129
	v_pk_mul_f32 v[134:135], v[76:77], v[134:135]
	v_pk_fma_f32 v[60:61], v[60:61], v[196:197], v[130:131]
	v_pk_fma_f32 v[56:57], v[56:57], v[192:193], v[132:133]
	s_waitcnt vmcnt(12)
	v_lshlrev_b32_e32 v136, 16, v122
	v_and_b32_e32 v137, 0xffff0000, v122
	v_pk_mul_f32 v[124:125], v[94:95], v[124:125]
	v_pk_mul_f32 v[126:127], v[74:75], v[126:127]
	v_pk_mul_f32 v[128:129], v[78:79], v[128:129]
	v_pk_fma_f32 v[52:53], v[52:53], v[188:189], v[134:135]
	v_mul_f32_e32 v122, v61, v61
	v_mul_f32_e32 v138, v57, v57
	v_pk_fma_f32 v[62:63], v[62:63], v[194:195], v[124:125]
	v_pk_fma_f32 v[58:59], v[58:59], v[190:191], v[126:127]
	v_pk_fma_f32 v[54:55], v[54:55], v[186:187], v[128:129]
	v_mul_f32_e32 v139, v53, v53
	v_fmac_f32_e32 v122, v60, v60
	v_fmac_f32_e32 v138, v56, v56
	v_pk_mul_f32 v[132:133], v[90:91], v[54:55]
	v_pk_mul_f32 v[134:135], v[88:89], v[52:53]
	v_fmac_f32_e32 v139, v52, v52
	v_fmac_f32_e32 v122, v62, v62
	v_fmac_f32_e32 v138, v58, v58
	v_pk_mul_f32 v[128:129], v[66:67], v[58:59]
	v_pk_mul_f32 v[130:131], v[64:65], v[56:57]
	v_cvt_pk_bf16_f32 v52, v134, v135
	v_cvt_pk_bf16_f32 v53, v132, v133
	v_fmac_f32_e32 v139, v54, v54
	v_fmac_f32_e32 v122, v63, v63
	v_fmac_f32_e32 v138, v59, v59
	v_cvt_pk_bf16_f32 v56, v130, v131
	v_cvt_pk_bf16_f32 v57, v128, v129
	global_store_dwordx2 v[118:119], v[52:53], off offset:256
	v_fmac_f32_e32 v139, v55, v55
	v_add_f32_e32 v52, v122, v138
	global_store_dwordx2 v[118:119], v[56:57], off offset:32
	v_add_f32_e32 v56, v52, v139
	v_lshlrev_b32_e32 v52, 16, v123
	v_and_b32_e32 v53, 0xffff0000, v123
	v_pk_mul_f32 v[54:55], v[80:81], v[136:137]
	v_pk_mul_f32 v[52:53], v[82:83], v[52:53]
	v_pk_fma_f32 v[48:49], v[48:49], v[184:185], v[54:55]
	v_pk_fma_f32 v[50:51], v[50:51], v[182:183], v[52:53]
	v_mul_f32_e32 v52, v49, v49
	v_fmac_f32_e32 v52, v48, v48
	v_fmac_f32_e32 v52, v50, v50
	v_fmac_f32_e32 v52, v51, v51
	v_pk_mul_f32 v[50:51], v[70:71], v[50:51]
	v_pk_mul_f32 v[48:49], v[68:69], v[48:49]
	v_add_f32_e32 v52, v56, v52
	v_cvt_pk_bf16_f32 v48, v48, v49
	v_cvt_pk_bf16_f32 v49, v50, v51
	global_store_dwordx2 v[118:119], v[48:49], off offset:288
	v_mov_b32_e32 v48, v52
	s_nop 1
	v_permlane16_swap_b32_e32 v52, v48
	v_add_f32_e32 v48, v52, v48
	v_pk_mul_f32 v[124:125], v[86:87], v[62:63]
	v_pk_mul_f32 v[126:127], v[84:85], v[60:61]
	v_mov_b32_e32 v49, v48
	v_cvt_pk_bf16_f32 v60, v126, v127
	v_cvt_pk_bf16_f32 v61, v124, v125
	v_permlane32_swap_b32_e32 v48, v49
	global_store_dwordx2 v[118:119], v[60:61], off
	s_and_saveexec_b64 s[58:59], s[14:15]
	s_cbranch_execz .LBB0_1827
	v_add_f32_e32 v48, v48, v49
	global_atomic_add_f32 v[174:175], v48, off offset:512
